# combine pass: 4 rows (12 loads) in flight per wave instead of 8
# speedup vs baseline: 1.0006x; 1.0006x over previous
.Lcomb:
	s_mov_b64 exec, -1
	v_lshlrev_b32_e32 v132, 5, v240
	v_lshlrev_b32_e32 v128, 4, v240
	global_load_dwordx4 v[120:123], v132, s[62:63]
	global_load_dwordx4 v[124:127], v132, s[62:63] offset:16
	s_lshl_b32 s98, s74, 10
	v_add_u32_e32 v133, s98, v128
	s_mul_i32 s98, s74, 0xe00
	s_addk_i32 s98, 0xa00
	v_add_u32_e32 v134, s98, v128
	s_lshl_b32 s98, s74, 11
	s_addk_i32 s98, 0x400
	v_add_u32_e32 v135, s98, v128
	v_mov_b32_e32 v140, 0xbdd2d3e8
	v_mov_b32_e32 v142, 0xc0135761
	v_mov_b32_e32 v131, 0x358637bd
	global_load_dwordx4 v[0:3], v133, s[22:23] nt
	global_load_dwordx4 v[4:7], v133, s[20:21] nt
	global_load_dwordx4 v[8:11], v134, s[38:39] nt
	v_add_u32_e32 v136, 0x200000, v133
	v_add_u32_e32 v137, 0x700000, v134
	global_load_dwordx4 v[12:15], v136, s[22:23] nt
	global_load_dwordx4 v[16:19], v136, s[20:21] nt
	global_load_dwordx4 v[20:23], v137, s[38:39] nt
	v_add_u32_e32 v136, 0x400000, v133
	v_add_u32_e32 v137, 0xe00000, v134
	global_load_dwordx4 v[24:27], v136, s[22:23] nt
	global_load_dwordx4 v[28:31], v136, s[20:21] nt
	global_load_dwordx4 v[32:35], v137, s[38:39] nt
	v_add_u32_e32 v136, 0x600000, v133
	v_add_u32_e32 v137, 0x1500000, v134
	global_load_dwordx4 v[36:39], v136, s[22:23] nt
	global_load_dwordx4 v[40:43], v136, s[20:21] nt
	global_load_dwordx4 v[44:47], v137, s[38:39] nt
	s_waitcnt vmcnt(9)
	v_lshlrev_b32_e32 v146, 16, v0
	v_and_b32_e32 v147, 0xffff0000, v0
	v_lshlrev_b32_e32 v148, 16, v1
	v_and_b32_e32 v149, 0xffff0000, v1
	v_lshlrev_b32_e32 v150, 16, v2
	v_and_b32_e32 v151, 0xffff0000, v2
	v_lshlrev_b32_e32 v152, 16, v3
	v_and_b32_e32 v153, 0xffff0000, v3
	v_lshlrev_b32_e32 v154, 16, v4
	v_and_b32_e32 v155, 0xffff0000, v4
	v_lshlrev_b32_e32 v156, 16, v5
	v_and_b32_e32 v157, 0xffff0000, v5
	v_lshlrev_b32_e32 v158, 16, v6
	v_and_b32_e32 v159, 0xffff0000, v6
	v_lshlrev_b32_e32 v160, 16, v7
	v_and_b32_e32 v161, 0xffff0000, v7
	v_lshlrev_b32_e32 v162, 16, v8
	v_and_b32_e32 v163, 0xffff0000, v8
	v_lshlrev_b32_e32 v164, 16, v9
	v_and_b32_e32 v165, 0xffff0000, v9
	v_lshlrev_b32_e32 v166, 16, v10
	v_and_b32_e32 v167, 0xffff0000, v10
	v_lshlrev_b32_e32 v168, 16, v11
	v_and_b32_e32 v169, 0xffff0000, v11
	v_pk_add_f32 v[146:147], v[146:147], v[154:155]
	v_pk_add_f32 v[148:149], v[148:149], v[156:157]
	v_pk_add_f32 v[150:151], v[150:151], v[158:159]
	v_pk_add_f32 v[152:153], v[152:153], v[160:161]
	v_pk_mul_f32 v[170:171], v[162:163], v[162:163]
	v_pk_mul_f32 v[172:173], v[164:165], v[164:165]
	v_pk_mul_f32 v[174:175], v[166:167], v[166:167]
	v_pk_mul_f32 v[176:177], v[168:169], v[168:169]
	v_pk_fma_f32 v[170:171], v[170:171], v[140:141], v[142:143] op_sel_hi:[1,0,0]
	v_pk_fma_f32 v[172:173], v[172:173], v[140:141], v[142:143] op_sel_hi:[1,0,0]
	v_pk_fma_f32 v[174:175], v[174:175], v[140:141], v[142:143] op_sel_hi:[1,0,0]
	v_pk_fma_f32 v[176:177], v[176:177], v[140:141], v[142:143] op_sel_hi:[1,0,0]
	v_pk_mul_f32 v[170:171], v[170:171], v[162:163]
	v_pk_mul_f32 v[172:173], v[172:173], v[164:165]
	v_pk_mul_f32 v[174:175], v[174:175], v[166:167]
	v_pk_mul_f32 v[176:177], v[176:177], v[168:169]
	v_pk_mul_f32 v[154:155], v[146:147], v[162:163]
	v_pk_mul_f32 v[156:157], v[148:149], v[164:165]
	v_pk_mul_f32 v[158:159], v[150:151], v[166:167]
	v_pk_mul_f32 v[160:161], v[152:153], v[168:169]
	v_exp_f32_e32 v170, v170
	v_exp_f32_e32 v171, v171
	v_exp_f32_e32 v172, v172
	v_exp_f32_e32 v173, v173
	v_exp_f32_e32 v174, v174
	v_exp_f32_e32 v175, v175
	v_exp_f32_e32 v176, v176
	v_exp_f32_e32 v177, v177
	v_pk_add_f32 v[170:171], v[170:171], 1.0 op_sel_hi:[1,0]
	v_pk_add_f32 v[172:173], v[172:173], 1.0 op_sel_hi:[1,0]
	v_pk_add_f32 v[174:175], v[174:175], 1.0 op_sel_hi:[1,0]
	v_pk_add_f32 v[176:177], v[176:177], 1.0 op_sel_hi:[1,0]
	v_rcp_f32_e32 v170, v170
	v_rcp_f32_e32 v171, v171
	v_rcp_f32_e32 v172, v172
	v_rcp_f32_e32 v173, v173
	v_rcp_f32_e32 v174, v174
	v_rcp_f32_e32 v175, v175
	v_rcp_f32_e32 v176, v176
	v_rcp_f32_e32 v177, v177
	v_pk_mul_f32 v[96:97], v[154:155], v[170:171]
	v_pk_mul_f32 v[98:99], v[156:157], v[172:173]
	v_pk_mul_f32 v[100:101], v[158:159], v[174:175]
	v_pk_mul_f32 v[102:103], v[160:161], v[176:177]
	v_pk_mul_f32 v[112:113], v[96:97], v[96:97]
	v_pk_mul_f32 v[114:115], v[98:99], v[98:99]
	v_pk_fma_f32 v[112:113], v[100:101], v[100:101], v[112:113]
	v_pk_fma_f32 v[114:115], v[102:103], v[102:103], v[114:115]
	v_pk_add_f32 v[112:113], v[112:113], v[114:115]
	v_add_f32_e32 v112, v112, v113
	v_pk_mul_f32 v[146:147], v[96:97], v[120:121]
	v_pk_mul_f32 v[148:149], v[98:99], v[122:123]
	v_add_f32_dpp v112, v112, v112 quad_perm:[1,0,3,2] row_mask:0xf bank_mask:0xf
	v_pk_mul_f32 v[150:151], v[100:101], v[124:125]
	v_pk_mul_f32 v[152:153], v[102:103], v[126:127]
	v_add_f32_dpp v112, v112, v112 quad_perm:[2,3,0,1] row_mask:0xf bank_mask:0xf
	s_nop 1
	v_add_f32_dpp v112, v112, v112 row_half_mirror row_mask:0xf bank_mask:0xf
	s_nop 1
	v_add_f32_dpp v112, v112, v112 row_mirror row_mask:0xf bank_mask:0xf
	s_nop 1
	v_readlane_b32 s98, v112, 0
	v_readlane_b32 s99, v112, 16
	v_readlane_b32 s100, v112, 32
	v_readlane_b32 vcc_lo, v112, 48
	s_nop 1
	v_mov_b32_e32 v113, s98
	v_add_f32_e32 v113, s99, v113
	v_add_f32_e32 v113, s100, v113
	v_add_f32_e32 v113, vcc_lo, v113
	v_fmamk_f32 v144, v113, 0x3b000000, v131
	v_rsq_f32_e32 v144, v144
	s_nop 0
	v_pk_mul_f32 v[146:147], v[146:147], v[144:145] op_sel_hi:[1,0]
	v_pk_mul_f32 v[148:149], v[148:149], v[144:145] op_sel_hi:[1,0]
	v_pk_mul_f32 v[150:151], v[150:151], v[144:145] op_sel_hi:[1,0]
	v_pk_mul_f32 v[152:153], v[152:153], v[144:145] op_sel_hi:[1,0]
	v_cvt_pk_bf16_f32 v116, v146, v147
	v_cvt_pk_bf16_f32 v117, v148, v149
	v_cvt_pk_bf16_f32 v118, v150, v151
	v_cvt_pk_bf16_f32 v119, v152, v153
	global_store_dwordx4 v135, v[116:119], s[34:35]
	v_add_u32_e32 v136, 0x800000, v133
	v_add_u32_e32 v137, 0x1c00000, v134
	global_load_dwordx4 v[0:3], v136, s[22:23] nt
	global_load_dwordx4 v[4:7], v136, s[20:21] nt
	global_load_dwordx4 v[8:11], v137, s[38:39] nt
	s_waitcnt vmcnt(10)
	v_lshlrev_b32_e32 v146, 16, v12
	v_and_b32_e32 v147, 0xffff0000, v12
	v_lshlrev_b32_e32 v148, 16, v13
	v_and_b32_e32 v149, 0xffff0000, v13
	v_lshlrev_b32_e32 v150, 16, v14
	v_and_b32_e32 v151, 0xffff0000, v14
	v_lshlrev_b32_e32 v152, 16, v15
	v_and_b32_e32 v153, 0xffff0000, v15
	v_lshlrev_b32_e32 v154, 16, v16
	v_and_b32_e32 v155, 0xffff0000, v16
	v_lshlrev_b32_e32 v156, 16, v17
	v_and_b32_e32 v157, 0xffff0000, v17
	v_lshlrev_b32_e32 v158, 16, v18
	v_and_b32_e32 v159, 0xffff0000, v18
	v_lshlrev_b32_e32 v160, 16, v19
	v_and_b32_e32 v161, 0xffff0000, v19
	v_lshlrev_b32_e32 v162, 16, v20
	v_and_b32_e32 v163, 0xffff0000, v20
	v_lshlrev_b32_e32 v164, 16, v21
	v_and_b32_e32 v165, 0xffff0000, v21
	v_lshlrev_b32_e32 v166, 16, v22
	v_and_b32_e32 v167, 0xffff0000, v22
	v_lshlrev_b32_e32 v168, 16, v23
	v_and_b32_e32 v169, 0xffff0000, v23
	v_pk_add_f32 v[146:147], v[146:147], v[154:155]
	v_pk_add_f32 v[148:149], v[148:149], v[156:157]
	v_pk_add_f32 v[150:151], v[150:151], v[158:159]
	v_pk_add_f32 v[152:153], v[152:153], v[160:161]
	v_pk_mul_f32 v[170:171], v[162:163], v[162:163]
	v_pk_mul_f32 v[172:173], v[164:165], v[164:165]
	v_pk_mul_f32 v[174:175], v[166:167], v[166:167]
	v_pk_mul_f32 v[176:177], v[168:169], v[168:169]
	v_pk_fma_f32 v[170:171], v[170:171], v[140:141], v[142:143] op_sel_hi:[1,0,0]
	v_pk_fma_f32 v[172:173], v[172:173], v[140:141], v[142:143] op_sel_hi:[1,0,0]
	v_pk_fma_f32 v[174:175], v[174:175], v[140:141], v[142:143] op_sel_hi:[1,0,0]
	v_pk_fma_f32 v[176:177], v[176:177], v[140:141], v[142:143] op_sel_hi:[1,0,0]
	v_pk_mul_f32 v[170:171], v[170:171], v[162:163]
	v_pk_mul_f32 v[172:173], v[172:173], v[164:165]
	v_pk_mul_f32 v[174:175], v[174:175], v[166:167]
	v_pk_mul_f32 v[176:177], v[176:177], v[168:169]
	v_pk_mul_f32 v[154:155], v[146:147], v[162:163]
	v_pk_mul_f32 v[156:157], v[148:149], v[164:165]
	v_pk_mul_f32 v[158:159], v[150:151], v[166:167]
	v_pk_mul_f32 v[160:161], v[152:153], v[168:169]
	v_exp_f32_e32 v170, v170
	v_exp_f32_e32 v171, v171
	v_exp_f32_e32 v172, v172
	v_exp_f32_e32 v173, v173
	v_exp_f32_e32 v174, v174
	v_exp_f32_e32 v175, v175
	v_exp_f32_e32 v176, v176
	v_exp_f32_e32 v177, v177
	v_pk_add_f32 v[170:171], v[170:171], 1.0 op_sel_hi:[1,0]
	v_pk_add_f32 v[172:173], v[172:173], 1.0 op_sel_hi:[1,0]
	v_pk_add_f32 v[174:175], v[174:175], 1.0 op_sel_hi:[1,0]
	v_pk_add_f32 v[176:177], v[176:177], 1.0 op_sel_hi:[1,0]
	v_rcp_f32_e32 v170, v170
	v_rcp_f32_e32 v171, v171
	v_rcp_f32_e32 v172, v172
	v_rcp_f32_e32 v173, v173
	v_rcp_f32_e32 v174, v174
	v_rcp_f32_e32 v175, v175
	v_rcp_f32_e32 v176, v176
	v_rcp_f32_e32 v177, v177
	v_pk_mul_f32 v[96:97], v[154:155], v[170:171]
	v_pk_mul_f32 v[98:99], v[156:157], v[172:173]
	v_pk_mul_f32 v[100:101], v[158:159], v[174:175]
	v_pk_mul_f32 v[102:103], v[160:161], v[176:177]
	v_pk_mul_f32 v[112:113], v[96:97], v[96:97]
	v_pk_mul_f32 v[114:115], v[98:99], v[98:99]
	v_pk_fma_f32 v[112:113], v[100:101], v[100:101], v[112:113]
	v_pk_fma_f32 v[114:115], v[102:103], v[102:103], v[114:115]
	v_pk_add_f32 v[112:113], v[112:113], v[114:115]
	v_add_f32_e32 v112, v112, v113
	v_pk_mul_f32 v[146:147], v[96:97], v[120:121]
	v_pk_mul_f32 v[148:149], v[98:99], v[122:123]
	v_add_f32_dpp v112, v112, v112 quad_perm:[1,0,3,2] row_mask:0xf bank_mask:0xf
	v_pk_mul_f32 v[150:151], v[100:101], v[124:125]
	v_pk_mul_f32 v[152:153], v[102:103], v[126:127]
	v_add_f32_dpp v112, v112, v112 quad_perm:[2,3,0,1] row_mask:0xf bank_mask:0xf
	s_nop 1
	v_add_f32_dpp v112, v112, v112 row_half_mirror row_mask:0xf bank_mask:0xf
	s_nop 1
	v_add_f32_dpp v112, v112, v112 row_mirror row_mask:0xf bank_mask:0xf
	s_nop 1
	v_readlane_b32 s98, v112, 0
	v_readlane_b32 s99, v112, 16
	v_readlane_b32 s100, v112, 32
	v_readlane_b32 vcc_lo, v112, 48
	s_nop 1
	v_mov_b32_e32 v113, s98
	v_add_f32_e32 v113, s99, v113
	v_add_f32_e32 v113, s100, v113
	v_add_f32_e32 v113, vcc_lo, v113
	v_fmamk_f32 v144, v113, 0x3b000000, v131
	v_rsq_f32_e32 v144, v144
	s_nop 0
	v_pk_mul_f32 v[146:147], v[146:147], v[144:145] op_sel_hi:[1,0]
	v_pk_mul_f32 v[148:149], v[148:149], v[144:145] op_sel_hi:[1,0]
	v_pk_mul_f32 v[150:151], v[150:151], v[144:145] op_sel_hi:[1,0]
	v_pk_mul_f32 v[152:153], v[152:153], v[144:145] op_sel_hi:[1,0]
	v_cvt_pk_bf16_f32 v116, v146, v147
	v_cvt_pk_bf16_f32 v117, v148, v149
	v_cvt_pk_bf16_f32 v118, v150, v151
	v_cvt_pk_bf16_f32 v119, v152, v153
	v_add_u32_e32 v138, 0x400000, v135
	global_store_dwordx4 v138, v[116:119], s[34:35]
	v_add_u32_e32 v136, 0xa00000, v133
	v_add_u32_e32 v137, 0x2300000, v134
	global_load_dwordx4 v[12:15], v136, s[22:23] nt
	global_load_dwordx4 v[16:19], v136, s[20:21] nt
	global_load_dwordx4 v[20:23], v137, s[38:39] nt
	s_waitcnt vmcnt(11)
	v_lshlrev_b32_e32 v146, 16, v24
	v_and_b32_e32 v147, 0xffff0000, v24
	v_lshlrev_b32_e32 v148, 16, v25
	v_and_b32_e32 v149, 0xffff0000, v25
	v_lshlrev_b32_e32 v150, 16, v26
	v_and_b32_e32 v151, 0xffff0000, v26
	v_lshlrev_b32_e32 v152, 16, v27
	v_and_b32_e32 v153, 0xffff0000, v27
	v_lshlrev_b32_e32 v154, 16, v28
	v_and_b32_e32 v155, 0xffff0000, v28
	v_lshlrev_b32_e32 v156, 16, v29
	v_and_b32_e32 v157, 0xffff0000, v29
	v_lshlrev_b32_e32 v158, 16, v30
	v_and_b32_e32 v159, 0xffff0000, v30
	v_lshlrev_b32_e32 v160, 16, v31
	v_and_b32_e32 v161, 0xffff0000, v31
	v_lshlrev_b32_e32 v162, 16, v32
	v_and_b32_e32 v163, 0xffff0000, v32
	v_lshlrev_b32_e32 v164, 16, v33
	v_and_b32_e32 v165, 0xffff0000, v33
	v_lshlrev_b32_e32 v166, 16, v34
	v_and_b32_e32 v167, 0xffff0000, v34
	v_lshlrev_b32_e32 v168, 16, v35
	v_and_b32_e32 v169, 0xffff0000, v35
	v_pk_add_f32 v[146:147], v[146:147], v[154:155]
	v_pk_add_f32 v[148:149], v[148:149], v[156:157]
	v_pk_add_f32 v[150:151], v[150:151], v[158:159]
	v_pk_add_f32 v[152:153], v[152:153], v[160:161]
	v_pk_mul_f32 v[170:171], v[162:163], v[162:163]
	v_pk_mul_f32 v[172:173], v[164:165], v[164:165]
	v_pk_mul_f32 v[174:175], v[166:167], v[166:167]
	v_pk_mul_f32 v[176:177], v[168:169], v[168:169]
	v_pk_fma_f32 v[170:171], v[170:171], v[140:141], v[142:143] op_sel_hi:[1,0,0]
	v_pk_fma_f32 v[172:173], v[172:173], v[140:141], v[142:143] op_sel_hi:[1,0,0]
	v_pk_fma_f32 v[174:175], v[174:175], v[140:141], v[142:143] op_sel_hi:[1,0,0]
	v_pk_fma_f32 v[176:177], v[176:177], v[140:141], v[142:143] op_sel_hi:[1,0,0]
	v_pk_mul_f32 v[170:171], v[170:171], v[162:163]
	v_pk_mul_f32 v[172:173], v[172:173], v[164:165]
	v_pk_mul_f32 v[174:175], v[174:175], v[166:167]
	v_pk_mul_f32 v[176:177], v[176:177], v[168:169]
	v_pk_mul_f32 v[154:155], v[146:147], v[162:163]
	v_pk_mul_f32 v[156:157], v[148:149], v[164:165]
	v_pk_mul_f32 v[158:159], v[150:151], v[166:167]
	v_pk_mul_f32 v[160:161], v[152:153], v[168:169]
	v_exp_f32_e32 v170, v170
	v_exp_f32_e32 v171, v171
	v_exp_f32_e32 v172, v172
	v_exp_f32_e32 v173, v173
	v_exp_f32_e32 v174, v174
	v_exp_f32_e32 v175, v175
	v_exp_f32_e32 v176, v176
	v_exp_f32_e32 v177, v177
	v_pk_add_f32 v[170:171], v[170:171], 1.0 op_sel_hi:[1,0]
	v_pk_add_f32 v[172:173], v[172:173], 1.0 op_sel_hi:[1,0]
	v_pk_add_f32 v[174:175], v[174:175], 1.0 op_sel_hi:[1,0]
	v_pk_add_f32 v[176:177], v[176:177], 1.0 op_sel_hi:[1,0]
	v_rcp_f32_e32 v170, v170
	v_rcp_f32_e32 v171, v171
	v_rcp_f32_e32 v172, v172
	v_rcp_f32_e32 v173, v173
	v_rcp_f32_e32 v174, v174
	v_rcp_f32_e32 v175, v175
	v_rcp_f32_e32 v176, v176
	v_rcp_f32_e32 v177, v177
	v_pk_mul_f32 v[96:97], v[154:155], v[170:171]
	v_pk_mul_f32 v[98:99], v[156:157], v[172:173]
	v_pk_mul_f32 v[100:101], v[158:159], v[174:175]
	v_pk_mul_f32 v[102:103], v[160:161], v[176:177]
	v_pk_mul_f32 v[112:113], v[96:97], v[96:97]
	v_pk_mul_f32 v[114:115], v[98:99], v[98:99]
	v_pk_fma_f32 v[112:113], v[100:101], v[100:101], v[112:113]
	v_pk_fma_f32 v[114:115], v[102:103], v[102:103], v[114:115]
	v_pk_add_f32 v[112:113], v[112:113], v[114:115]
	v_add_f32_e32 v112, v112, v113
	v_pk_mul_f32 v[146:147], v[96:97], v[120:121]
	v_pk_mul_f32 v[148:149], v[98:99], v[122:123]
	v_add_f32_dpp v112, v112, v112 quad_perm:[1,0,3,2] row_mask:0xf bank_mask:0xf
	v_pk_mul_f32 v[150:151], v[100:101], v[124:125]
	v_pk_mul_f32 v[152:153], v[102:103], v[126:127]
	v_add_f32_dpp v112, v112, v112 quad_perm:[2,3,0,1] row_mask:0xf bank_mask:0xf
	s_nop 1
	v_add_f32_dpp v112, v112, v112 row_half_mirror row_mask:0xf bank_mask:0xf
	s_nop 1
	v_add_f32_dpp v112, v112, v112 row_mirror row_mask:0xf bank_mask:0xf
	s_nop 1
	v_readlane_b32 s98, v112, 0
	v_readlane_b32 s99, v112, 16
	v_readlane_b32 s100, v112, 32
	v_readlane_b32 vcc_lo, v112, 48
	s_nop 1
	v_mov_b32_e32 v113, s98
	v_add_f32_e32 v113, s99, v113
	v_add_f32_e32 v113, s100, v113
	v_add_f32_e32 v113, vcc_lo, v113
	v_fmamk_f32 v144, v113, 0x3b000000, v131
	v_rsq_f32_e32 v144, v144
	s_nop 0
	v_pk_mul_f32 v[146:147], v[146:147], v[144:145] op_sel_hi:[1,0]
	v_pk_mul_f32 v[148:149], v[148:149], v[144:145] op_sel_hi:[1,0]
	v_pk_mul_f32 v[150:151], v[150:151], v[144:145] op_sel_hi:[1,0]
	v_pk_mul_f32 v[152:153], v[152:153], v[144:145] op_sel_hi:[1,0]
	v_cvt_pk_bf16_f32 v116, v146, v147
	v_cvt_pk_bf16_f32 v117, v148, v149
	v_cvt_pk_bf16_f32 v118, v150, v151
	v_cvt_pk_bf16_f32 v119, v152, v153
	v_add_u32_e32 v138, 0x800000, v135
	global_store_dwordx4 v138, v[116:119], s[34:35]
	v_add_u32_e32 v136, 0xc00000, v133
	v_add_u32_e32 v137, 0x2a00000, v134
	global_load_dwordx4 v[24:27], v136, s[22:23] nt
	global_load_dwordx4 v[28:31], v136, s[20:21] nt
	global_load_dwordx4 v[32:35], v137, s[38:39] nt
	s_waitcnt vmcnt(12)
	v_lshlrev_b32_e32 v146, 16, v36
	v_and_b32_e32 v147, 0xffff0000, v36
	v_lshlrev_b32_e32 v148, 16, v37
	v_and_b32_e32 v149, 0xffff0000, v37
	v_lshlrev_b32_e32 v150, 16, v38
	v_and_b32_e32 v151, 0xffff0000, v38
	v_lshlrev_b32_e32 v152, 16, v39
	v_and_b32_e32 v153, 0xffff0000, v39
	v_lshlrev_b32_e32 v154, 16, v40
	v_and_b32_e32 v155, 0xffff0000, v40
	v_lshlrev_b32_e32 v156, 16, v41
	v_and_b32_e32 v157, 0xffff0000, v41
	v_lshlrev_b32_e32 v158, 16, v42
	v_and_b32_e32 v159, 0xffff0000, v42
	v_lshlrev_b32_e32 v160, 16, v43
	v_and_b32_e32 v161, 0xffff0000, v43
	v_lshlrev_b32_e32 v162, 16, v44
	v_and_b32_e32 v163, 0xffff0000, v44
	v_lshlrev_b32_e32 v164, 16, v45
	v_and_b32_e32 v165, 0xffff0000, v45
	v_lshlrev_b32_e32 v166, 16, v46
	v_and_b32_e32 v167, 0xffff0000, v46
	v_lshlrev_b32_e32 v168, 16, v47
	v_and_b32_e32 v169, 0xffff0000, v47
	v_pk_add_f32 v[146:147], v[146:147], v[154:155]
	v_pk_add_f32 v[148:149], v[148:149], v[156:157]
	v_pk_add_f32 v[150:151], v[150:151], v[158:159]
	v_pk_add_f32 v[152:153], v[152:153], v[160:161]
	v_pk_mul_f32 v[170:171], v[162:163], v[162:163]
	v_pk_mul_f32 v[172:173], v[164:165], v[164:165]
	v_pk_mul_f32 v[174:175], v[166:167], v[166:167]
	v_pk_mul_f32 v[176:177], v[168:169], v[168:169]
	v_pk_fma_f32 v[170:171], v[170:171], v[140:141], v[142:143] op_sel_hi:[1,0,0]
	v_pk_fma_f32 v[172:173], v[172:173], v[140:141], v[142:143] op_sel_hi:[1,0,0]
	v_pk_fma_f32 v[174:175], v[174:175], v[140:141], v[142:143] op_sel_hi:[1,0,0]
	v_pk_fma_f32 v[176:177], v[176:177], v[140:141], v[142:143] op_sel_hi:[1,0,0]
	v_pk_mul_f32 v[170:171], v[170:171], v[162:163]
	v_pk_mul_f32 v[172:173], v[172:173], v[164:165]
	v_pk_mul_f32 v[174:175], v[174:175], v[166:167]
	v_pk_mul_f32 v[176:177], v[176:177], v[168:169]
	v_pk_mul_f32 v[154:155], v[146:147], v[162:163]
	v_pk_mul_f32 v[156:157], v[148:149], v[164:165]
	v_pk_mul_f32 v[158:159], v[150:151], v[166:167]
	v_pk_mul_f32 v[160:161], v[152:153], v[168:169]
	v_exp_f32_e32 v170, v170
	v_exp_f32_e32 v171, v171
	v_exp_f32_e32 v172, v172
	v_exp_f32_e32 v173, v173
	v_exp_f32_e32 v174, v174
	v_exp_f32_e32 v175, v175
	v_exp_f32_e32 v176, v176
	v_exp_f32_e32 v177, v177
	v_pk_add_f32 v[170:171], v[170:171], 1.0 op_sel_hi:[1,0]
	v_pk_add_f32 v[172:173], v[172:173], 1.0 op_sel_hi:[1,0]
	v_pk_add_f32 v[174:175], v[174:175], 1.0 op_sel_hi:[1,0]
	v_pk_add_f32 v[176:177], v[176:177], 1.0 op_sel_hi:[1,0]
	v_rcp_f32_e32 v170, v170
	v_rcp_f32_e32 v171, v171
	v_rcp_f32_e32 v172, v172
	v_rcp_f32_e32 v173, v173
	v_rcp_f32_e32 v174, v174
	v_rcp_f32_e32 v175, v175
	v_rcp_f32_e32 v176, v176
	v_rcp_f32_e32 v177, v177
	v_pk_mul_f32 v[96:97], v[154:155], v[170:171]
	v_pk_mul_f32 v[98:99], v[156:157], v[172:173]
	v_pk_mul_f32 v[100:101], v[158:159], v[174:175]
	v_pk_mul_f32 v[102:103], v[160:161], v[176:177]
	v_pk_mul_f32 v[112:113], v[96:97], v[96:97]
	v_pk_mul_f32 v[114:115], v[98:99], v[98:99]
	v_pk_fma_f32 v[112:113], v[100:101], v[100:101], v[112:113]
	v_pk_fma_f32 v[114:115], v[102:103], v[102:103], v[114:115]
	v_pk_add_f32 v[112:113], v[112:113], v[114:115]
	v_add_f32_e32 v112, v112, v113
	v_pk_mul_f32 v[146:147], v[96:97], v[120:121]
	v_pk_mul_f32 v[148:149], v[98:99], v[122:123]
	v_add_f32_dpp v112, v112, v112 quad_perm:[1,0,3,2] row_mask:0xf bank_mask:0xf
	v_pk_mul_f32 v[150:151], v[100:101], v[124:125]
	v_pk_mul_f32 v[152:153], v[102:103], v[126:127]
	v_add_f32_dpp v112, v112, v112 quad_perm:[2,3,0,1] row_mask:0xf bank_mask:0xf
	s_nop 1
	v_add_f32_dpp v112, v112, v112 row_half_mirror row_mask:0xf bank_mask:0xf
	s_nop 1
	v_add_f32_dpp v112, v112, v112 row_mirror row_mask:0xf bank_mask:0xf
	s_nop 1
	v_readlane_b32 s98, v112, 0
	v_readlane_b32 s99, v112, 16
	v_readlane_b32 s100, v112, 32
	v_readlane_b32 vcc_lo, v112, 48
	s_nop 1
	v_mov_b32_e32 v113, s98
	v_add_f32_e32 v113, s99, v113
	v_add_f32_e32 v113, s100, v113
	v_add_f32_e32 v113, vcc_lo, v113
	v_fmamk_f32 v144, v113, 0x3b000000, v131
	v_rsq_f32_e32 v144, v144
	s_nop 0
	v_pk_mul_f32 v[146:147], v[146:147], v[144:145] op_sel_hi:[1,0]
	v_pk_mul_f32 v[148:149], v[148:149], v[144:145] op_sel_hi:[1,0]
	v_pk_mul_f32 v[150:151], v[150:151], v[144:145] op_sel_hi:[1,0]
	v_pk_mul_f32 v[152:153], v[152:153], v[144:145] op_sel_hi:[1,0]
	v_cvt_pk_bf16_f32 v116, v146, v147
	v_cvt_pk_bf16_f32 v117, v148, v149
	v_cvt_pk_bf16_f32 v118, v150, v151
	v_cvt_pk_bf16_f32 v119, v152, v153
	v_add_u32_e32 v138, 0xc00000, v135
	global_store_dwordx4 v138, v[116:119], s[34:35]
	v_add_u32_e32 v136, 0xe00000, v133
	v_add_u32_e32 v137, 0x3100000, v134
	global_load_dwordx4 v[36:39], v136, s[22:23] nt
	global_load_dwordx4 v[40:43], v136, s[20:21] nt
	global_load_dwordx4 v[44:47], v137, s[38:39] nt
	s_waitcnt vmcnt(12)
	v_lshlrev_b32_e32 v146, 16, v0
	v_and_b32_e32 v147, 0xffff0000, v0
	v_lshlrev_b32_e32 v148, 16, v1
	v_and_b32_e32 v149, 0xffff0000, v1
	v_lshlrev_b32_e32 v150, 16, v2
	v_and_b32_e32 v151, 0xffff0000, v2
	v_lshlrev_b32_e32 v152, 16, v3
	v_and_b32_e32 v153, 0xffff0000, v3
	v_lshlrev_b32_e32 v154, 16, v4
	v_and_b32_e32 v155, 0xffff0000, v4
	v_lshlrev_b32_e32 v156, 16, v5
	v_and_b32_e32 v157, 0xffff0000, v5
	v_lshlrev_b32_e32 v158, 16, v6
	v_and_b32_e32 v159, 0xffff0000, v6
	v_lshlrev_b32_e32 v160, 16, v7
	v_and_b32_e32 v161, 0xffff0000, v7
	v_lshlrev_b32_e32 v162, 16, v8
	v_and_b32_e32 v163, 0xffff0000, v8
	v_lshlrev_b32_e32 v164, 16, v9
	v_and_b32_e32 v165, 0xffff0000, v9
	v_lshlrev_b32_e32 v166, 16, v10
	v_and_b32_e32 v167, 0xffff0000, v10
	v_lshlrev_b32_e32 v168, 16, v11
	v_and_b32_e32 v169, 0xffff0000, v11
	v_pk_add_f32 v[146:147], v[146:147], v[154:155]
	v_pk_add_f32 v[148:149], v[148:149], v[156:157]
	v_pk_add_f32 v[150:151], v[150:151], v[158:159]
	v_pk_add_f32 v[152:153], v[152:153], v[160:161]
	v_pk_mul_f32 v[170:171], v[162:163], v[162:163]
	v_pk_mul_f32 v[172:173], v[164:165], v[164:165]
	v_pk_mul_f32 v[174:175], v[166:167], v[166:167]
	v_pk_mul_f32 v[176:177], v[168:169], v[168:169]
	v_pk_fma_f32 v[170:171], v[170:171], v[140:141], v[142:143] op_sel_hi:[1,0,0]
	v_pk_fma_f32 v[172:173], v[172:173], v[140:141], v[142:143] op_sel_hi:[1,0,0]
	v_pk_fma_f32 v[174:175], v[174:175], v[140:141], v[142:143] op_sel_hi:[1,0,0]
	v_pk_fma_f32 v[176:177], v[176:177], v[140:141], v[142:143] op_sel_hi:[1,0,0]
	v_pk_mul_f32 v[170:171], v[170:171], v[162:163]
	v_pk_mul_f32 v[172:173], v[172:173], v[164:165]
	v_pk_mul_f32 v[174:175], v[174:175], v[166:167]
	v_pk_mul_f32 v[176:177], v[176:177], v[168:169]
	v_pk_mul_f32 v[154:155], v[146:147], v[162:163]
	v_pk_mul_f32 v[156:157], v[148:149], v[164:165]
	v_pk_mul_f32 v[158:159], v[150:151], v[166:167]
	v_pk_mul_f32 v[160:161], v[152:153], v[168:169]
	v_exp_f32_e32 v170, v170
	v_exp_f32_e32 v171, v171
	v_exp_f32_e32 v172, v172
	v_exp_f32_e32 v173, v173
	v_exp_f32_e32 v174, v174
	v_exp_f32_e32 v175, v175
	v_exp_f32_e32 v176, v176
	v_exp_f32_e32 v177, v177
	v_pk_add_f32 v[170:171], v[170:171], 1.0 op_sel_hi:[1,0]
	v_pk_add_f32 v[172:173], v[172:173], 1.0 op_sel_hi:[1,0]
	v_pk_add_f32 v[174:175], v[174:175], 1.0 op_sel_hi:[1,0]
	v_pk_add_f32 v[176:177], v[176:177], 1.0 op_sel_hi:[1,0]
	v_rcp_f32_e32 v170, v170
	v_rcp_f32_e32 v171, v171
	v_rcp_f32_e32 v172, v172
	v_rcp_f32_e32 v173, v173
	v_rcp_f32_e32 v174, v174
	v_rcp_f32_e32 v175, v175
	v_rcp_f32_e32 v176, v176
	v_rcp_f32_e32 v177, v177
	v_pk_mul_f32 v[96:97], v[154:155], v[170:171]
	v_pk_mul_f32 v[98:99], v[156:157], v[172:173]
	v_pk_mul_f32 v[100:101], v[158:159], v[174:175]
	v_pk_mul_f32 v[102:103], v[160:161], v[176:177]
	v_pk_mul_f32 v[112:113], v[96:97], v[96:97]
	v_pk_mul_f32 v[114:115], v[98:99], v[98:99]
	v_pk_fma_f32 v[112:113], v[100:101], v[100:101], v[112:113]
	v_pk_fma_f32 v[114:115], v[102:103], v[102:103], v[114:115]
	v_pk_add_f32 v[112:113], v[112:113], v[114:115]
	v_add_f32_e32 v112, v112, v113
	v_pk_mul_f32 v[146:147], v[96:97], v[120:121]
	v_pk_mul_f32 v[148:149], v[98:99], v[122:123]
	v_add_f32_dpp v112, v112, v112 quad_perm:[1,0,3,2] row_mask:0xf bank_mask:0xf
	v_pk_mul_f32 v[150:151], v[100:101], v[124:125]
	v_pk_mul_f32 v[152:153], v[102:103], v[126:127]
	v_add_f32_dpp v112, v112, v112 quad_perm:[2,3,0,1] row_mask:0xf bank_mask:0xf
	s_nop 1
	v_add_f32_dpp v112, v112, v112 row_half_mirror row_mask:0xf bank_mask:0xf
	s_nop 1
	v_add_f32_dpp v112, v112, v112 row_mirror row_mask:0xf bank_mask:0xf
	s_nop 1
	v_readlane_b32 s98, v112, 0
	v_readlane_b32 s99, v112, 16
	v_readlane_b32 s100, v112, 32
	v_readlane_b32 vcc_lo, v112, 48
	s_nop 1
	v_mov_b32_e32 v113, s98
	v_add_f32_e32 v113, s99, v113
	v_add_f32_e32 v113, s100, v113
	v_add_f32_e32 v113, vcc_lo, v113
	v_fmamk_f32 v144, v113, 0x3b000000, v131
	v_rsq_f32_e32 v144, v144
	s_nop 0
	v_pk_mul_f32 v[146:147], v[146:147], v[144:145] op_sel_hi:[1,0]
	v_pk_mul_f32 v[148:149], v[148:149], v[144:145] op_sel_hi:[1,0]
	v_pk_mul_f32 v[150:151], v[150:151], v[144:145] op_sel_hi:[1,0]
	v_pk_mul_f32 v[152:153], v[152:153], v[144:145] op_sel_hi:[1,0]
	v_cvt_pk_bf16_f32 v116, v146, v147
	v_cvt_pk_bf16_f32 v117, v148, v149
	v_cvt_pk_bf16_f32 v118, v150, v151
	v_cvt_pk_bf16_f32 v119, v152, v153
	v_add_u32_e32 v138, 0x1000000, v135
	global_store_dwordx4 v138, v[116:119], s[34:35]
	v_add_u32_e32 v136, 0x1000000, v133
	v_add_u32_e32 v137, 0x3800000, v134
	global_load_dwordx4 v[0:3], v136, s[22:23] nt
	global_load_dwordx4 v[4:7], v136, s[20:21] nt
	global_load_dwordx4 v[8:11], v137, s[38:39] nt
	s_waitcnt vmcnt(12)
	v_lshlrev_b32_e32 v146, 16, v12
	v_and_b32_e32 v147, 0xffff0000, v12
	v_lshlrev_b32_e32 v148, 16, v13
	v_and_b32_e32 v149, 0xffff0000, v13
	v_lshlrev_b32_e32 v150, 16, v14
	v_and_b32_e32 v151, 0xffff0000, v14
	v_lshlrev_b32_e32 v152, 16, v15
	v_and_b32_e32 v153, 0xffff0000, v15
	v_lshlrev_b32_e32 v154, 16, v16
	v_and_b32_e32 v155, 0xffff0000, v16
	v_lshlrev_b32_e32 v156, 16, v17
	v_and_b32_e32 v157, 0xffff0000, v17
	v_lshlrev_b32_e32 v158, 16, v18
	v_and_b32_e32 v159, 0xffff0000, v18
	v_lshlrev_b32_e32 v160, 16, v19
	v_and_b32_e32 v161, 0xffff0000, v19
	v_lshlrev_b32_e32 v162, 16, v20
	v_and_b32_e32 v163, 0xffff0000, v20
	v_lshlrev_b32_e32 v164, 16, v21
	v_and_b32_e32 v165, 0xffff0000, v21
	v_lshlrev_b32_e32 v166, 16, v22
	v_and_b32_e32 v167, 0xffff0000, v22
	v_lshlrev_b32_e32 v168, 16, v23
	v_and_b32_e32 v169, 0xffff0000, v23
	v_pk_add_f32 v[146:147], v[146:147], v[154:155]
	v_pk_add_f32 v[148:149], v[148:149], v[156:157]
	v_pk_add_f32 v[150:151], v[150:151], v[158:159]
	v_pk_add_f32 v[152:153], v[152:153], v[160:161]
	v_pk_mul_f32 v[170:171], v[162:163], v[162:163]
	v_pk_mul_f32 v[172:173], v[164:165], v[164:165]
	v_pk_mul_f32 v[174:175], v[166:167], v[166:167]
	v_pk_mul_f32 v[176:177], v[168:169], v[168:169]
	v_pk_fma_f32 v[170:171], v[170:171], v[140:141], v[142:143] op_sel_hi:[1,0,0]
	v_pk_fma_f32 v[172:173], v[172:173], v[140:141], v[142:143] op_sel_hi:[1,0,0]
	v_pk_fma_f32 v[174:175], v[174:175], v[140:141], v[142:143] op_sel_hi:[1,0,0]
	v_pk_fma_f32 v[176:177], v[176:177], v[140:141], v[142:143] op_sel_hi:[1,0,0]
	v_pk_mul_f32 v[170:171], v[170:171], v[162:163]
	v_pk_mul_f32 v[172:173], v[172:173], v[164:165]
	v_pk_mul_f32 v[174:175], v[174:175], v[166:167]
	v_pk_mul_f32 v[176:177], v[176:177], v[168:169]
	v_pk_mul_f32 v[154:155], v[146:147], v[162:163]
	v_pk_mul_f32 v[156:157], v[148:149], v[164:165]
	v_pk_mul_f32 v[158:159], v[150:151], v[166:167]
	v_pk_mul_f32 v[160:161], v[152:153], v[168:169]
	v_exp_f32_e32 v170, v170
	v_exp_f32_e32 v171, v171
	v_exp_f32_e32 v172, v172
	v_exp_f32_e32 v173, v173
	v_exp_f32_e32 v174, v174
	v_exp_f32_e32 v175, v175
	v_exp_f32_e32 v176, v176
	v_exp_f32_e32 v177, v177
	v_pk_add_f32 v[170:171], v[170:171], 1.0 op_sel_hi:[1,0]
	v_pk_add_f32 v[172:173], v[172:173], 1.0 op_sel_hi:[1,0]
	v_pk_add_f32 v[174:175], v[174:175], 1.0 op_sel_hi:[1,0]
	v_pk_add_f32 v[176:177], v[176:177], 1.0 op_sel_hi:[1,0]
	v_rcp_f32_e32 v170, v170
	v_rcp_f32_e32 v171, v171
	v_rcp_f32_e32 v172, v172
	v_rcp_f32_e32 v173, v173
	v_rcp_f32_e32 v174, v174
	v_rcp_f32_e32 v175, v175
	v_rcp_f32_e32 v176, v176
	v_rcp_f32_e32 v177, v177
	v_pk_mul_f32 v[96:97], v[154:155], v[170:171]
	v_pk_mul_f32 v[98:99], v[156:157], v[172:173]
	v_pk_mul_f32 v[100:101], v[158:159], v[174:175]
	v_pk_mul_f32 v[102:103], v[160:161], v[176:177]
	v_pk_mul_f32 v[112:113], v[96:97], v[96:97]
	v_pk_mul_f32 v[114:115], v[98:99], v[98:99]
	v_pk_fma_f32 v[112:113], v[100:101], v[100:101], v[112:113]
	v_pk_fma_f32 v[114:115], v[102:103], v[102:103], v[114:115]
	v_pk_add_f32 v[112:113], v[112:113], v[114:115]
	v_add_f32_e32 v112, v112, v113
	v_pk_mul_f32 v[146:147], v[96:97], v[120:121]
	v_pk_mul_f32 v[148:149], v[98:99], v[122:123]
	v_add_f32_dpp v112, v112, v112 quad_perm:[1,0,3,2] row_mask:0xf bank_mask:0xf
	v_pk_mul_f32 v[150:151], v[100:101], v[124:125]
	v_pk_mul_f32 v[152:153], v[102:103], v[126:127]
	v_add_f32_dpp v112, v112, v112 quad_perm:[2,3,0,1] row_mask:0xf bank_mask:0xf
	s_nop 1
	v_add_f32_dpp v112, v112, v112 row_half_mirror row_mask:0xf bank_mask:0xf
	s_nop 1
	v_add_f32_dpp v112, v112, v112 row_mirror row_mask:0xf bank_mask:0xf
	s_nop 1
	v_readlane_b32 s98, v112, 0
	v_readlane_b32 s99, v112, 16
	v_readlane_b32 s100, v112, 32
	v_readlane_b32 vcc_lo, v112, 48
	s_nop 1
	v_mov_b32_e32 v113, s98
	v_add_f32_e32 v113, s99, v113
	v_add_f32_e32 v113, s100, v113
	v_add_f32_e32 v113, vcc_lo, v113
	v_fmamk_f32 v144, v113, 0x3b000000, v131
	v_rsq_f32_e32 v144, v144
	s_nop 0
	v_pk_mul_f32 v[146:147], v[146:147], v[144:145] op_sel_hi:[1,0]
	v_pk_mul_f32 v[148:149], v[148:149], v[144:145] op_sel_hi:[1,0]
	v_pk_mul_f32 v[150:151], v[150:151], v[144:145] op_sel_hi:[1,0]
	v_pk_mul_f32 v[152:153], v[152:153], v[144:145] op_sel_hi:[1,0]
	v_cvt_pk_bf16_f32 v116, v146, v147
	v_cvt_pk_bf16_f32 v117, v148, v149
	v_cvt_pk_bf16_f32 v118, v150, v151
	v_cvt_pk_bf16_f32 v119, v152, v153
	v_add_u32_e32 v138, 0x1400000, v135
	global_store_dwordx4 v138, v[116:119], s[34:35]
	v_add_u32_e32 v136, 0x1200000, v133
	v_add_u32_e32 v137, 0x3f00000, v134
	global_load_dwordx4 v[12:15], v136, s[22:23] nt
	global_load_dwordx4 v[16:19], v136, s[20:21] nt
	global_load_dwordx4 v[20:23], v137, s[38:39] nt
	s_waitcnt vmcnt(12)
	v_lshlrev_b32_e32 v146, 16, v24
	v_and_b32_e32 v147, 0xffff0000, v24
	v_lshlrev_b32_e32 v148, 16, v25
	v_and_b32_e32 v149, 0xffff0000, v25
	v_lshlrev_b32_e32 v150, 16, v26
	v_and_b32_e32 v151, 0xffff0000, v26
	v_lshlrev_b32_e32 v152, 16, v27
	v_and_b32_e32 v153, 0xffff0000, v27
	v_lshlrev_b32_e32 v154, 16, v28
	v_and_b32_e32 v155, 0xffff0000, v28
	v_lshlrev_b32_e32 v156, 16, v29
	v_and_b32_e32 v157, 0xffff0000, v29
	v_lshlrev_b32_e32 v158, 16, v30
	v_and_b32_e32 v159, 0xffff0000, v30
	v_lshlrev_b32_e32 v160, 16, v31
	v_and_b32_e32 v161, 0xffff0000, v31
	v_lshlrev_b32_e32 v162, 16, v32
	v_and_b32_e32 v163, 0xffff0000, v32
	v_lshlrev_b32_e32 v164, 16, v33
	v_and_b32_e32 v165, 0xffff0000, v33
	v_lshlrev_b32_e32 v166, 16, v34
	v_and_b32_e32 v167, 0xffff0000, v34
	v_lshlrev_b32_e32 v168, 16, v35
	v_and_b32_e32 v169, 0xffff0000, v35
	v_pk_add_f32 v[146:147], v[146:147], v[154:155]
	v_pk_add_f32 v[148:149], v[148:149], v[156:157]
	v_pk_add_f32 v[150:151], v[150:151], v[158:159]
	v_pk_add_f32 v[152:153], v[152:153], v[160:161]
	v_pk_mul_f32 v[170:171], v[162:163], v[162:163]
	v_pk_mul_f32 v[172:173], v[164:165], v[164:165]
	v_pk_mul_f32 v[174:175], v[166:167], v[166:167]
	v_pk_mul_f32 v[176:177], v[168:169], v[168:169]
	v_pk_fma_f32 v[170:171], v[170:171], v[140:141], v[142:143] op_sel_hi:[1,0,0]
	v_pk_fma_f32 v[172:173], v[172:173], v[140:141], v[142:143] op_sel_hi:[1,0,0]
	v_pk_fma_f32 v[174:175], v[174:175], v[140:141], v[142:143] op_sel_hi:[1,0,0]
	v_pk_fma_f32 v[176:177], v[176:177], v[140:141], v[142:143] op_sel_hi:[1,0,0]
	v_pk_mul_f32 v[170:171], v[170:171], v[162:163]
	v_pk_mul_f32 v[172:173], v[172:173], v[164:165]
	v_pk_mul_f32 v[174:175], v[174:175], v[166:167]
	v_pk_mul_f32 v[176:177], v[176:177], v[168:169]
	v_pk_mul_f32 v[154:155], v[146:147], v[162:163]
	v_pk_mul_f32 v[156:157], v[148:149], v[164:165]
	v_pk_mul_f32 v[158:159], v[150:151], v[166:167]
	v_pk_mul_f32 v[160:161], v[152:153], v[168:169]
	v_exp_f32_e32 v170, v170
	v_exp_f32_e32 v171, v171
	v_exp_f32_e32 v172, v172
	v_exp_f32_e32 v173, v173
	v_exp_f32_e32 v174, v174
	v_exp_f32_e32 v175, v175
	v_exp_f32_e32 v176, v176
	v_exp_f32_e32 v177, v177
	v_pk_add_f32 v[170:171], v[170:171], 1.0 op_sel_hi:[1,0]
	v_pk_add_f32 v[172:173], v[172:173], 1.0 op_sel_hi:[1,0]
	v_pk_add_f32 v[174:175], v[174:175], 1.0 op_sel_hi:[1,0]
	v_pk_add_f32 v[176:177], v[176:177], 1.0 op_sel_hi:[1,0]
	v_rcp_f32_e32 v170, v170
	v_rcp_f32_e32 v171, v171
	v_rcp_f32_e32 v172, v172
	v_rcp_f32_e32 v173, v173
	v_rcp_f32_e32 v174, v174
	v_rcp_f32_e32 v175, v175
	v_rcp_f32_e32 v176, v176
	v_rcp_f32_e32 v177, v177
	v_pk_mul_f32 v[96:97], v[154:155], v[170:171]
	v_pk_mul_f32 v[98:99], v[156:157], v[172:173]
	v_pk_mul_f32 v[100:101], v[158:159], v[174:175]
	v_pk_mul_f32 v[102:103], v[160:161], v[176:177]
	v_pk_mul_f32 v[112:113], v[96:97], v[96:97]
	v_pk_mul_f32 v[114:115], v[98:99], v[98:99]
	v_pk_fma_f32 v[112:113], v[100:101], v[100:101], v[112:113]
	v_pk_fma_f32 v[114:115], v[102:103], v[102:103], v[114:115]
	v_pk_add_f32 v[112:113], v[112:113], v[114:115]
	v_add_f32_e32 v112, v112, v113
	v_pk_mul_f32 v[146:147], v[96:97], v[120:121]
	v_pk_mul_f32 v[148:149], v[98:99], v[122:123]
	v_add_f32_dpp v112, v112, v112 quad_perm:[1,0,3,2] row_mask:0xf bank_mask:0xf
	v_pk_mul_f32 v[150:151], v[100:101], v[124:125]
	v_pk_mul_f32 v[152:153], v[102:103], v[126:127]
	v_add_f32_dpp v112, v112, v112 quad_perm:[2,3,0,1] row_mask:0xf bank_mask:0xf
	s_nop 1
	v_add_f32_dpp v112, v112, v112 row_half_mirror row_mask:0xf bank_mask:0xf
	s_nop 1
	v_add_f32_dpp v112, v112, v112 row_mirror row_mask:0xf bank_mask:0xf
	s_nop 1
	v_readlane_b32 s98, v112, 0
	v_readlane_b32 s99, v112, 16
	v_readlane_b32 s100, v112, 32
	v_readlane_b32 vcc_lo, v112, 48
	s_nop 1
	v_mov_b32_e32 v113, s98
	v_add_f32_e32 v113, s99, v113
	v_add_f32_e32 v113, s100, v113
	v_add_f32_e32 v113, vcc_lo, v113
	v_fmamk_f32 v144, v113, 0x3b000000, v131
	v_rsq_f32_e32 v144, v144
	s_nop 0
	v_pk_mul_f32 v[146:147], v[146:147], v[144:145] op_sel_hi:[1,0]
	v_pk_mul_f32 v[148:149], v[148:149], v[144:145] op_sel_hi:[1,0]
	v_pk_mul_f32 v[150:151], v[150:151], v[144:145] op_sel_hi:[1,0]
	v_pk_mul_f32 v[152:153], v[152:153], v[144:145] op_sel_hi:[1,0]
	v_cvt_pk_bf16_f32 v116, v146, v147
	v_cvt_pk_bf16_f32 v117, v148, v149
	v_cvt_pk_bf16_f32 v118, v150, v151
	v_cvt_pk_bf16_f32 v119, v152, v153
	v_add_u32_e32 v138, 0x1800000, v135
	global_store_dwordx4 v138, v[116:119], s[34:35]
	v_add_u32_e32 v136, 0x1400000, v133
	v_add_u32_e32 v137, 0x4600000, v134
	global_load_dwordx4 v[24:27], v136, s[22:23] nt
	global_load_dwordx4 v[28:31], v136, s[20:21] nt
	global_load_dwordx4 v[32:35], v137, s[38:39] nt
	s_waitcnt vmcnt(12)
	v_lshlrev_b32_e32 v146, 16, v36
	v_and_b32_e32 v147, 0xffff0000, v36
	v_lshlrev_b32_e32 v148, 16, v37
	v_and_b32_e32 v149, 0xffff0000, v37
	v_lshlrev_b32_e32 v150, 16, v38
	v_and_b32_e32 v151, 0xffff0000, v38
	v_lshlrev_b32_e32 v152, 16, v39
	v_and_b32_e32 v153, 0xffff0000, v39
	v_lshlrev_b32_e32 v154, 16, v40
	v_and_b32_e32 v155, 0xffff0000, v40
	v_lshlrev_b32_e32 v156, 16, v41
	v_and_b32_e32 v157, 0xffff0000, v41
	v_lshlrev_b32_e32 v158, 16, v42
	v_and_b32_e32 v159, 0xffff0000, v42
	v_lshlrev_b32_e32 v160, 16, v43
	v_and_b32_e32 v161, 0xffff0000, v43
	v_lshlrev_b32_e32 v162, 16, v44
	v_and_b32_e32 v163, 0xffff0000, v44
	v_lshlrev_b32_e32 v164, 16, v45
	v_and_b32_e32 v165, 0xffff0000, v45
	v_lshlrev_b32_e32 v166, 16, v46
	v_and_b32_e32 v167, 0xffff0000, v46
	v_lshlrev_b32_e32 v168, 16, v47
	v_and_b32_e32 v169, 0xffff0000, v47
	v_pk_add_f32 v[146:147], v[146:147], v[154:155]
	v_pk_add_f32 v[148:149], v[148:149], v[156:157]
	v_pk_add_f32 v[150:151], v[150:151], v[158:159]
	v_pk_add_f32 v[152:153], v[152:153], v[160:161]
	v_pk_mul_f32 v[170:171], v[162:163], v[162:163]
	v_pk_mul_f32 v[172:173], v[164:165], v[164:165]
	v_pk_mul_f32 v[174:175], v[166:167], v[166:167]
	v_pk_mul_f32 v[176:177], v[168:169], v[168:169]
	v_pk_fma_f32 v[170:171], v[170:171], v[140:141], v[142:143] op_sel_hi:[1,0,0]
	v_pk_fma_f32 v[172:173], v[172:173], v[140:141], v[142:143] op_sel_hi:[1,0,0]
	v_pk_fma_f32 v[174:175], v[174:175], v[140:141], v[142:143] op_sel_hi:[1,0,0]
	v_pk_fma_f32 v[176:177], v[176:177], v[140:141], v[142:143] op_sel_hi:[1,0,0]
	v_pk_mul_f32 v[170:171], v[170:171], v[162:163]
	v_pk_mul_f32 v[172:173], v[172:173], v[164:165]
	v_pk_mul_f32 v[174:175], v[174:175], v[166:167]
	v_pk_mul_f32 v[176:177], v[176:177], v[168:169]
	v_pk_mul_f32 v[154:155], v[146:147], v[162:163]
	v_pk_mul_f32 v[156:157], v[148:149], v[164:165]
	v_pk_mul_f32 v[158:159], v[150:151], v[166:167]
	v_pk_mul_f32 v[160:161], v[152:153], v[168:169]
	v_exp_f32_e32 v170, v170
	v_exp_f32_e32 v171, v171
	v_exp_f32_e32 v172, v172
	v_exp_f32_e32 v173, v173
	v_exp_f32_e32 v174, v174
	v_exp_f32_e32 v175, v175
	v_exp_f32_e32 v176, v176
	v_exp_f32_e32 v177, v177
	v_pk_add_f32 v[170:171], v[170:171], 1.0 op_sel_hi:[1,0]
	v_pk_add_f32 v[172:173], v[172:173], 1.0 op_sel_hi:[1,0]
	v_pk_add_f32 v[174:175], v[174:175], 1.0 op_sel_hi:[1,0]
	v_pk_add_f32 v[176:177], v[176:177], 1.0 op_sel_hi:[1,0]
	v_rcp_f32_e32 v170, v170
	v_rcp_f32_e32 v171, v171
	v_rcp_f32_e32 v172, v172
	v_rcp_f32_e32 v173, v173
	v_rcp_f32_e32 v174, v174
	v_rcp_f32_e32 v175, v175
	v_rcp_f32_e32 v176, v176
	v_rcp_f32_e32 v177, v177
	v_pk_mul_f32 v[96:97], v[154:155], v[170:171]
	v_pk_mul_f32 v[98:99], v[156:157], v[172:173]
	v_pk_mul_f32 v[100:101], v[158:159], v[174:175]
	v_pk_mul_f32 v[102:103], v[160:161], v[176:177]
	v_pk_mul_f32 v[112:113], v[96:97], v[96:97]
	v_pk_mul_f32 v[114:115], v[98:99], v[98:99]
	v_pk_fma_f32 v[112:113], v[100:101], v[100:101], v[112:113]
	v_pk_fma_f32 v[114:115], v[102:103], v[102:103], v[114:115]
	v_pk_add_f32 v[112:113], v[112:113], v[114:115]
	v_add_f32_e32 v112, v112, v113
	v_pk_mul_f32 v[146:147], v[96:97], v[120:121]
	v_pk_mul_f32 v[148:149], v[98:99], v[122:123]
	v_add_f32_dpp v112, v112, v112 quad_perm:[1,0,3,2] row_mask:0xf bank_mask:0xf
	v_pk_mul_f32 v[150:151], v[100:101], v[124:125]
	v_pk_mul_f32 v[152:153], v[102:103], v[126:127]
	v_add_f32_dpp v112, v112, v112 quad_perm:[2,3,0,1] row_mask:0xf bank_mask:0xf
	s_nop 1
	v_add_f32_dpp v112, v112, v112 row_half_mirror row_mask:0xf bank_mask:0xf
	s_nop 1
	v_add_f32_dpp v112, v112, v112 row_mirror row_mask:0xf bank_mask:0xf
	s_nop 1
	v_readlane_b32 s98, v112, 0
	v_readlane_b32 s99, v112, 16
	v_readlane_b32 s100, v112, 32
	v_readlane_b32 vcc_lo, v112, 48
	s_nop 1
	v_mov_b32_e32 v113, s98
	v_add_f32_e32 v113, s99, v113
	v_add_f32_e32 v113, s100, v113
	v_add_f32_e32 v113, vcc_lo, v113
	v_fmamk_f32 v144, v113, 0x3b000000, v131
	v_rsq_f32_e32 v144, v144
	s_nop 0
	v_pk_mul_f32 v[146:147], v[146:147], v[144:145] op_sel_hi:[1,0]
	v_pk_mul_f32 v[148:149], v[148:149], v[144:145] op_sel_hi:[1,0]
	v_pk_mul_f32 v[150:151], v[150:151], v[144:145] op_sel_hi:[1,0]
	v_pk_mul_f32 v[152:153], v[152:153], v[144:145] op_sel_hi:[1,0]
	v_cvt_pk_bf16_f32 v116, v146, v147
	v_cvt_pk_bf16_f32 v117, v148, v149
	v_cvt_pk_bf16_f32 v118, v150, v151
	v_cvt_pk_bf16_f32 v119, v152, v153
	v_add_u32_e32 v138, 0x1c00000, v135
	global_store_dwordx4 v138, v[116:119], s[34:35]
	v_add_u32_e32 v136, 0x1600000, v133
	v_add_u32_e32 v137, 0x4d00000, v134
	global_load_dwordx4 v[36:39], v136, s[22:23] nt
	global_load_dwordx4 v[40:43], v136, s[20:21] nt
	global_load_dwordx4 v[44:47], v137, s[38:39] nt
	s_waitcnt vmcnt(12)
	v_lshlrev_b32_e32 v146, 16, v0
	v_and_b32_e32 v147, 0xffff0000, v0
	v_lshlrev_b32_e32 v148, 16, v1
	v_and_b32_e32 v149, 0xffff0000, v1
	v_lshlrev_b32_e32 v150, 16, v2
	v_and_b32_e32 v151, 0xffff0000, v2
	v_lshlrev_b32_e32 v152, 16, v3
	v_and_b32_e32 v153, 0xffff0000, v3
	v_lshlrev_b32_e32 v154, 16, v4
	v_and_b32_e32 v155, 0xffff0000, v4
	v_lshlrev_b32_e32 v156, 16, v5
	v_and_b32_e32 v157, 0xffff0000, v5
	v_lshlrev_b32_e32 v158, 16, v6
	v_and_b32_e32 v159, 0xffff0000, v6
	v_lshlrev_b32_e32 v160, 16, v7
	v_and_b32_e32 v161, 0xffff0000, v7
	v_lshlrev_b32_e32 v162, 16, v8
	v_and_b32_e32 v163, 0xffff0000, v8
	v_lshlrev_b32_e32 v164, 16, v9
	v_and_b32_e32 v165, 0xffff0000, v9
	v_lshlrev_b32_e32 v166, 16, v10
	v_and_b32_e32 v167, 0xffff0000, v10
	v_lshlrev_b32_e32 v168, 16, v11
	v_and_b32_e32 v169, 0xffff0000, v11
	v_pk_add_f32 v[146:147], v[146:147], v[154:155]
	v_pk_add_f32 v[148:149], v[148:149], v[156:157]
	v_pk_add_f32 v[150:151], v[150:151], v[158:159]
	v_pk_add_f32 v[152:153], v[152:153], v[160:161]
	v_pk_mul_f32 v[170:171], v[162:163], v[162:163]
	v_pk_mul_f32 v[172:173], v[164:165], v[164:165]
	v_pk_mul_f32 v[174:175], v[166:167], v[166:167]
	v_pk_mul_f32 v[176:177], v[168:169], v[168:169]
	v_pk_fma_f32 v[170:171], v[170:171], v[140:141], v[142:143] op_sel_hi:[1,0,0]
	v_pk_fma_f32 v[172:173], v[172:173], v[140:141], v[142:143] op_sel_hi:[1,0,0]
	v_pk_fma_f32 v[174:175], v[174:175], v[140:141], v[142:143] op_sel_hi:[1,0,0]
	v_pk_fma_f32 v[176:177], v[176:177], v[140:141], v[142:143] op_sel_hi:[1,0,0]
	v_pk_mul_f32 v[170:171], v[170:171], v[162:163]
	v_pk_mul_f32 v[172:173], v[172:173], v[164:165]
	v_pk_mul_f32 v[174:175], v[174:175], v[166:167]
	v_pk_mul_f32 v[176:177], v[176:177], v[168:169]
	v_pk_mul_f32 v[154:155], v[146:147], v[162:163]
	v_pk_mul_f32 v[156:157], v[148:149], v[164:165]
	v_pk_mul_f32 v[158:159], v[150:151], v[166:167]
	v_pk_mul_f32 v[160:161], v[152:153], v[168:169]
	v_exp_f32_e32 v170, v170
	v_exp_f32_e32 v171, v171
	v_exp_f32_e32 v172, v172
	v_exp_f32_e32 v173, v173
	v_exp_f32_e32 v174, v174
	v_exp_f32_e32 v175, v175
	v_exp_f32_e32 v176, v176
	v_exp_f32_e32 v177, v177
	v_pk_add_f32 v[170:171], v[170:171], 1.0 op_sel_hi:[1,0]
	v_pk_add_f32 v[172:173], v[172:173], 1.0 op_sel_hi:[1,0]
	v_pk_add_f32 v[174:175], v[174:175], 1.0 op_sel_hi:[1,0]
	v_pk_add_f32 v[176:177], v[176:177], 1.0 op_sel_hi:[1,0]
	v_rcp_f32_e32 v170, v170
	v_rcp_f32_e32 v171, v171
	v_rcp_f32_e32 v172, v172
	v_rcp_f32_e32 v173, v173
	v_rcp_f32_e32 v174, v174
	v_rcp_f32_e32 v175, v175
	v_rcp_f32_e32 v176, v176
	v_rcp_f32_e32 v177, v177
	v_pk_mul_f32 v[96:97], v[154:155], v[170:171]
	v_pk_mul_f32 v[98:99], v[156:157], v[172:173]
	v_pk_mul_f32 v[100:101], v[158:159], v[174:175]
	v_pk_mul_f32 v[102:103], v[160:161], v[176:177]
	v_pk_mul_f32 v[112:113], v[96:97], v[96:97]
	v_pk_mul_f32 v[114:115], v[98:99], v[98:99]
	v_pk_fma_f32 v[112:113], v[100:101], v[100:101], v[112:113]
	v_pk_fma_f32 v[114:115], v[102:103], v[102:103], v[114:115]
	v_pk_add_f32 v[112:113], v[112:113], v[114:115]
	v_add_f32_e32 v112, v112, v113
	v_pk_mul_f32 v[146:147], v[96:97], v[120:121]
	v_pk_mul_f32 v[148:149], v[98:99], v[122:123]
	v_add_f32_dpp v112, v112, v112 quad_perm:[1,0,3,2] row_mask:0xf bank_mask:0xf
	v_pk_mul_f32 v[150:151], v[100:101], v[124:125]
	v_pk_mul_f32 v[152:153], v[102:103], v[126:127]
	v_add_f32_dpp v112, v112, v112 quad_perm:[2,3,0,1] row_mask:0xf bank_mask:0xf
	s_nop 1
	v_add_f32_dpp v112, v112, v112 row_half_mirror row_mask:0xf bank_mask:0xf
	s_nop 1
	v_add_f32_dpp v112, v112, v112 row_mirror row_mask:0xf bank_mask:0xf
	s_nop 1
	v_readlane_b32 s98, v112, 0
	v_readlane_b32 s99, v112, 16
	v_readlane_b32 s100, v112, 32
	v_readlane_b32 vcc_lo, v112, 48
	s_nop 1
	v_mov_b32_e32 v113, s98
	v_add_f32_e32 v113, s99, v113
	v_add_f32_e32 v113, s100, v113
	v_add_f32_e32 v113, vcc_lo, v113
	v_fmamk_f32 v144, v113, 0x3b000000, v131
	v_rsq_f32_e32 v144, v144
	s_nop 0
	v_pk_mul_f32 v[146:147], v[146:147], v[144:145] op_sel_hi:[1,0]
	v_pk_mul_f32 v[148:149], v[148:149], v[144:145] op_sel_hi:[1,0]
	v_pk_mul_f32 v[150:151], v[150:151], v[144:145] op_sel_hi:[1,0]
	v_pk_mul_f32 v[152:153], v[152:153], v[144:145] op_sel_hi:[1,0]
	v_cvt_pk_bf16_f32 v116, v146, v147
	v_cvt_pk_bf16_f32 v117, v148, v149
	v_cvt_pk_bf16_f32 v118, v150, v151
	v_cvt_pk_bf16_f32 v119, v152, v153
	v_add_u32_e32 v138, 0x2000000, v135
	global_store_dwordx4 v138, v[116:119], s[34:35]
	v_add_u32_e32 v136, 0x1800000, v133
	v_add_u32_e32 v137, 0x5400000, v134
	global_load_dwordx4 v[0:3], v136, s[22:23] nt
	global_load_dwordx4 v[4:7], v136, s[20:21] nt
	global_load_dwordx4 v[8:11], v137, s[38:39] nt
	s_waitcnt vmcnt(12)
	v_lshlrev_b32_e32 v146, 16, v12
	v_and_b32_e32 v147, 0xffff0000, v12
	v_lshlrev_b32_e32 v148, 16, v13
	v_and_b32_e32 v149, 0xffff0000, v13
	v_lshlrev_b32_e32 v150, 16, v14
	v_and_b32_e32 v151, 0xffff0000, v14
	v_lshlrev_b32_e32 v152, 16, v15
	v_and_b32_e32 v153, 0xffff0000, v15
	v_lshlrev_b32_e32 v154, 16, v16
	v_and_b32_e32 v155, 0xffff0000, v16
	v_lshlrev_b32_e32 v156, 16, v17
	v_and_b32_e32 v157, 0xffff0000, v17
	v_lshlrev_b32_e32 v158, 16, v18
	v_and_b32_e32 v159, 0xffff0000, v18
	v_lshlrev_b32_e32 v160, 16, v19
	v_and_b32_e32 v161, 0xffff0000, v19
	v_lshlrev_b32_e32 v162, 16, v20
	v_and_b32_e32 v163, 0xffff0000, v20
	v_lshlrev_b32_e32 v164, 16, v21
	v_and_b32_e32 v165, 0xffff0000, v21
	v_lshlrev_b32_e32 v166, 16, v22
	v_and_b32_e32 v167, 0xffff0000, v22
	v_lshlrev_b32_e32 v168, 16, v23
	v_and_b32_e32 v169, 0xffff0000, v23
	v_pk_add_f32 v[146:147], v[146:147], v[154:155]
	v_pk_add_f32 v[148:149], v[148:149], v[156:157]
	v_pk_add_f32 v[150:151], v[150:151], v[158:159]
	v_pk_add_f32 v[152:153], v[152:153], v[160:161]
	v_pk_mul_f32 v[170:171], v[162:163], v[162:163]
	v_pk_mul_f32 v[172:173], v[164:165], v[164:165]
	v_pk_mul_f32 v[174:175], v[166:167], v[166:167]
	v_pk_mul_f32 v[176:177], v[168:169], v[168:169]
	v_pk_fma_f32 v[170:171], v[170:171], v[140:141], v[142:143] op_sel_hi:[1,0,0]
	v_pk_fma_f32 v[172:173], v[172:173], v[140:141], v[142:143] op_sel_hi:[1,0,0]
	v_pk_fma_f32 v[174:175], v[174:175], v[140:141], v[142:143] op_sel_hi:[1,0,0]
	v_pk_fma_f32 v[176:177], v[176:177], v[140:141], v[142:143] op_sel_hi:[1,0,0]
	v_pk_mul_f32 v[170:171], v[170:171], v[162:163]
	v_pk_mul_f32 v[172:173], v[172:173], v[164:165]
	v_pk_mul_f32 v[174:175], v[174:175], v[166:167]
	v_pk_mul_f32 v[176:177], v[176:177], v[168:169]
	v_pk_mul_f32 v[154:155], v[146:147], v[162:163]
	v_pk_mul_f32 v[156:157], v[148:149], v[164:165]
	v_pk_mul_f32 v[158:159], v[150:151], v[166:167]
	v_pk_mul_f32 v[160:161], v[152:153], v[168:169]
	v_exp_f32_e32 v170, v170
	v_exp_f32_e32 v171, v171
	v_exp_f32_e32 v172, v172
	v_exp_f32_e32 v173, v173
	v_exp_f32_e32 v174, v174
	v_exp_f32_e32 v175, v175
	v_exp_f32_e32 v176, v176
	v_exp_f32_e32 v177, v177
	v_pk_add_f32 v[170:171], v[170:171], 1.0 op_sel_hi:[1,0]
	v_pk_add_f32 v[172:173], v[172:173], 1.0 op_sel_hi:[1,0]
	v_pk_add_f32 v[174:175], v[174:175], 1.0 op_sel_hi:[1,0]
	v_pk_add_f32 v[176:177], v[176:177], 1.0 op_sel_hi:[1,0]
	v_rcp_f32_e32 v170, v170
	v_rcp_f32_e32 v171, v171
	v_rcp_f32_e32 v172, v172
	v_rcp_f32_e32 v173, v173
	v_rcp_f32_e32 v174, v174
	v_rcp_f32_e32 v175, v175
	v_rcp_f32_e32 v176, v176
	v_rcp_f32_e32 v177, v177
	v_pk_mul_f32 v[96:97], v[154:155], v[170:171]
	v_pk_mul_f32 v[98:99], v[156:157], v[172:173]
	v_pk_mul_f32 v[100:101], v[158:159], v[174:175]
	v_pk_mul_f32 v[102:103], v[160:161], v[176:177]
	v_pk_mul_f32 v[112:113], v[96:97], v[96:97]
	v_pk_mul_f32 v[114:115], v[98:99], v[98:99]
	v_pk_fma_f32 v[112:113], v[100:101], v[100:101], v[112:113]
	v_pk_fma_f32 v[114:115], v[102:103], v[102:103], v[114:115]
	v_pk_add_f32 v[112:113], v[112:113], v[114:115]
	v_add_f32_e32 v112, v112, v113
	v_pk_mul_f32 v[146:147], v[96:97], v[120:121]
	v_pk_mul_f32 v[148:149], v[98:99], v[122:123]
	v_add_f32_dpp v112, v112, v112 quad_perm:[1,0,3,2] row_mask:0xf bank_mask:0xf
	v_pk_mul_f32 v[150:151], v[100:101], v[124:125]
	v_pk_mul_f32 v[152:153], v[102:103], v[126:127]
	v_add_f32_dpp v112, v112, v112 quad_perm:[2,3,0,1] row_mask:0xf bank_mask:0xf
	s_nop 1
	v_add_f32_dpp v112, v112, v112 row_half_mirror row_mask:0xf bank_mask:0xf
	s_nop 1
	v_add_f32_dpp v112, v112, v112 row_mirror row_mask:0xf bank_mask:0xf
	s_nop 1
	v_readlane_b32 s98, v112, 0
	v_readlane_b32 s99, v112, 16
	v_readlane_b32 s100, v112, 32
	v_readlane_b32 vcc_lo, v112, 48
	s_nop 1
	v_mov_b32_e32 v113, s98
	v_add_f32_e32 v113, s99, v113
	v_add_f32_e32 v113, s100, v113
	v_add_f32_e32 v113, vcc_lo, v113
	v_fmamk_f32 v144, v113, 0x3b000000, v131
	v_rsq_f32_e32 v144, v144
	s_nop 0
	v_pk_mul_f32 v[146:147], v[146:147], v[144:145] op_sel_hi:[1,0]
	v_pk_mul_f32 v[148:149], v[148:149], v[144:145] op_sel_hi:[1,0]
	v_pk_mul_f32 v[150:151], v[150:151], v[144:145] op_sel_hi:[1,0]
	v_pk_mul_f32 v[152:153], v[152:153], v[144:145] op_sel_hi:[1,0]
	v_cvt_pk_bf16_f32 v116, v146, v147
	v_cvt_pk_bf16_f32 v117, v148, v149
	v_cvt_pk_bf16_f32 v118, v150, v151
	v_cvt_pk_bf16_f32 v119, v152, v153
	v_add_u32_e32 v138, 0x2400000, v135
	global_store_dwordx4 v138, v[116:119], s[34:35]
	v_add_u32_e32 v136, 0x1a00000, v133
	v_add_u32_e32 v137, 0x5b00000, v134
	global_load_dwordx4 v[12:15], v136, s[22:23] nt
	global_load_dwordx4 v[16:19], v136, s[20:21] nt
	global_load_dwordx4 v[20:23], v137, s[38:39] nt
	s_waitcnt vmcnt(12)
	v_lshlrev_b32_e32 v146, 16, v24
	v_and_b32_e32 v147, 0xffff0000, v24
	v_lshlrev_b32_e32 v148, 16, v25
	v_and_b32_e32 v149, 0xffff0000, v25
	v_lshlrev_b32_e32 v150, 16, v26
	v_and_b32_e32 v151, 0xffff0000, v26
	v_lshlrev_b32_e32 v152, 16, v27
	v_and_b32_e32 v153, 0xffff0000, v27
	v_lshlrev_b32_e32 v154, 16, v28
	v_and_b32_e32 v155, 0xffff0000, v28
	v_lshlrev_b32_e32 v156, 16, v29
	v_and_b32_e32 v157, 0xffff0000, v29
	v_lshlrev_b32_e32 v158, 16, v30
	v_and_b32_e32 v159, 0xffff0000, v30
	v_lshlrev_b32_e32 v160, 16, v31
	v_and_b32_e32 v161, 0xffff0000, v31
	v_lshlrev_b32_e32 v162, 16, v32
	v_and_b32_e32 v163, 0xffff0000, v32
	v_lshlrev_b32_e32 v164, 16, v33
	v_and_b32_e32 v165, 0xffff0000, v33
	v_lshlrev_b32_e32 v166, 16, v34
	v_and_b32_e32 v167, 0xffff0000, v34
	v_lshlrev_b32_e32 v168, 16, v35
	v_and_b32_e32 v169, 0xffff0000, v35
	v_pk_add_f32 v[146:147], v[146:147], v[154:155]
	v_pk_add_f32 v[148:149], v[148:149], v[156:157]
	v_pk_add_f32 v[150:151], v[150:151], v[158:159]
	v_pk_add_f32 v[152:153], v[152:153], v[160:161]
	v_pk_mul_f32 v[170:171], v[162:163], v[162:163]
	v_pk_mul_f32 v[172:173], v[164:165], v[164:165]
	v_pk_mul_f32 v[174:175], v[166:167], v[166:167]
	v_pk_mul_f32 v[176:177], v[168:169], v[168:169]
	v_pk_fma_f32 v[170:171], v[170:171], v[140:141], v[142:143] op_sel_hi:[1,0,0]
	v_pk_fma_f32 v[172:173], v[172:173], v[140:141], v[142:143] op_sel_hi:[1,0,0]
	v_pk_fma_f32 v[174:175], v[174:175], v[140:141], v[142:143] op_sel_hi:[1,0,0]
	v_pk_fma_f32 v[176:177], v[176:177], v[140:141], v[142:143] op_sel_hi:[1,0,0]
	v_pk_mul_f32 v[170:171], v[170:171], v[162:163]
	v_pk_mul_f32 v[172:173], v[172:173], v[164:165]
	v_pk_mul_f32 v[174:175], v[174:175], v[166:167]
	v_pk_mul_f32 v[176:177], v[176:177], v[168:169]
	v_pk_mul_f32 v[154:155], v[146:147], v[162:163]
	v_pk_mul_f32 v[156:157], v[148:149], v[164:165]
	v_pk_mul_f32 v[158:159], v[150:151], v[166:167]
	v_pk_mul_f32 v[160:161], v[152:153], v[168:169]
	v_exp_f32_e32 v170, v170
	v_exp_f32_e32 v171, v171
	v_exp_f32_e32 v172, v172
	v_exp_f32_e32 v173, v173
	v_exp_f32_e32 v174, v174
	v_exp_f32_e32 v175, v175
	v_exp_f32_e32 v176, v176
	v_exp_f32_e32 v177, v177
	v_pk_add_f32 v[170:171], v[170:171], 1.0 op_sel_hi:[1,0]
	v_pk_add_f32 v[172:173], v[172:173], 1.0 op_sel_hi:[1,0]
	v_pk_add_f32 v[174:175], v[174:175], 1.0 op_sel_hi:[1,0]
	v_pk_add_f32 v[176:177], v[176:177], 1.0 op_sel_hi:[1,0]
	v_rcp_f32_e32 v170, v170
	v_rcp_f32_e32 v171, v171
	v_rcp_f32_e32 v172, v172
	v_rcp_f32_e32 v173, v173
	v_rcp_f32_e32 v174, v174
	v_rcp_f32_e32 v175, v175
	v_rcp_f32_e32 v176, v176
	v_rcp_f32_e32 v177, v177
	v_pk_mul_f32 v[96:97], v[154:155], v[170:171]
	v_pk_mul_f32 v[98:99], v[156:157], v[172:173]
	v_pk_mul_f32 v[100:101], v[158:159], v[174:175]
	v_pk_mul_f32 v[102:103], v[160:161], v[176:177]
	v_pk_mul_f32 v[112:113], v[96:97], v[96:97]
	v_pk_mul_f32 v[114:115], v[98:99], v[98:99]
	v_pk_fma_f32 v[112:113], v[100:101], v[100:101], v[112:113]
	v_pk_fma_f32 v[114:115], v[102:103], v[102:103], v[114:115]
	v_pk_add_f32 v[112:113], v[112:113], v[114:115]
	v_add_f32_e32 v112, v112, v113
	v_pk_mul_f32 v[146:147], v[96:97], v[120:121]
	v_pk_mul_f32 v[148:149], v[98:99], v[122:123]
	v_add_f32_dpp v112, v112, v112 quad_perm:[1,0,3,2] row_mask:0xf bank_mask:0xf
	v_pk_mul_f32 v[150:151], v[100:101], v[124:125]
	v_pk_mul_f32 v[152:153], v[102:103], v[126:127]
	v_add_f32_dpp v112, v112, v112 quad_perm:[2,3,0,1] row_mask:0xf bank_mask:0xf
	s_nop 1
	v_add_f32_dpp v112, v112, v112 row_half_mirror row_mask:0xf bank_mask:0xf
	s_nop 1
	v_add_f32_dpp v112, v112, v112 row_mirror row_mask:0xf bank_mask:0xf
	s_nop 1
	v_readlane_b32 s98, v112, 0
	v_readlane_b32 s99, v112, 16
	v_readlane_b32 s100, v112, 32
	v_readlane_b32 vcc_lo, v112, 48
	s_nop 1
	v_mov_b32_e32 v113, s98
	v_add_f32_e32 v113, s99, v113
	v_add_f32_e32 v113, s100, v113
	v_add_f32_e32 v113, vcc_lo, v113
	v_fmamk_f32 v144, v113, 0x3b000000, v131
	v_rsq_f32_e32 v144, v144
	s_nop 0
	v_pk_mul_f32 v[146:147], v[146:147], v[144:145] op_sel_hi:[1,0]
	v_pk_mul_f32 v[148:149], v[148:149], v[144:145] op_sel_hi:[1,0]
	v_pk_mul_f32 v[150:151], v[150:151], v[144:145] op_sel_hi:[1,0]
	v_pk_mul_f32 v[152:153], v[152:153], v[144:145] op_sel_hi:[1,0]
	v_cvt_pk_bf16_f32 v116, v146, v147
	v_cvt_pk_bf16_f32 v117, v148, v149
	v_cvt_pk_bf16_f32 v118, v150, v151
	v_cvt_pk_bf16_f32 v119, v152, v153
	v_add_u32_e32 v138, 0x2800000, v135
	global_store_dwordx4 v138, v[116:119], s[34:35]
	v_add_u32_e32 v136, 0x1c00000, v133
	v_add_u32_e32 v137, 0x6200000, v134
	global_load_dwordx4 v[24:27], v136, s[22:23] nt
	global_load_dwordx4 v[28:31], v136, s[20:21] nt
	global_load_dwordx4 v[32:35], v137, s[38:39] nt
	s_waitcnt vmcnt(12)
	v_lshlrev_b32_e32 v146, 16, v36
	v_and_b32_e32 v147, 0xffff0000, v36
	v_lshlrev_b32_e32 v148, 16, v37
	v_and_b32_e32 v149, 0xffff0000, v37
	v_lshlrev_b32_e32 v150, 16, v38
	v_and_b32_e32 v151, 0xffff0000, v38
	v_lshlrev_b32_e32 v152, 16, v39
	v_and_b32_e32 v153, 0xffff0000, v39
	v_lshlrev_b32_e32 v154, 16, v40
	v_and_b32_e32 v155, 0xffff0000, v40
	v_lshlrev_b32_e32 v156, 16, v41
	v_and_b32_e32 v157, 0xffff0000, v41
	v_lshlrev_b32_e32 v158, 16, v42
	v_and_b32_e32 v159, 0xffff0000, v42
	v_lshlrev_b32_e32 v160, 16, v43
	v_and_b32_e32 v161, 0xffff0000, v43
	v_lshlrev_b32_e32 v162, 16, v44
	v_and_b32_e32 v163, 0xffff0000, v44
	v_lshlrev_b32_e32 v164, 16, v45
	v_and_b32_e32 v165, 0xffff0000, v45
	v_lshlrev_b32_e32 v166, 16, v46
	v_and_b32_e32 v167, 0xffff0000, v46
	v_lshlrev_b32_e32 v168, 16, v47
	v_and_b32_e32 v169, 0xffff0000, v47
	v_pk_add_f32 v[146:147], v[146:147], v[154:155]
	v_pk_add_f32 v[148:149], v[148:149], v[156:157]
	v_pk_add_f32 v[150:151], v[150:151], v[158:159]
	v_pk_add_f32 v[152:153], v[152:153], v[160:161]
	v_pk_mul_f32 v[170:171], v[162:163], v[162:163]
	v_pk_mul_f32 v[172:173], v[164:165], v[164:165]
	v_pk_mul_f32 v[174:175], v[166:167], v[166:167]
	v_pk_mul_f32 v[176:177], v[168:169], v[168:169]
	v_pk_fma_f32 v[170:171], v[170:171], v[140:141], v[142:143] op_sel_hi:[1,0,0]
	v_pk_fma_f32 v[172:173], v[172:173], v[140:141], v[142:143] op_sel_hi:[1,0,0]
	v_pk_fma_f32 v[174:175], v[174:175], v[140:141], v[142:143] op_sel_hi:[1,0,0]
	v_pk_fma_f32 v[176:177], v[176:177], v[140:141], v[142:143] op_sel_hi:[1,0,0]
	v_pk_mul_f32 v[170:171], v[170:171], v[162:163]
	v_pk_mul_f32 v[172:173], v[172:173], v[164:165]
	v_pk_mul_f32 v[174:175], v[174:175], v[166:167]
	v_pk_mul_f32 v[176:177], v[176:177], v[168:169]
	v_pk_mul_f32 v[154:155], v[146:147], v[162:163]
	v_pk_mul_f32 v[156:157], v[148:149], v[164:165]
	v_pk_mul_f32 v[158:159], v[150:151], v[166:167]
	v_pk_mul_f32 v[160:161], v[152:153], v[168:169]
	v_exp_f32_e32 v170, v170
	v_exp_f32_e32 v171, v171
	v_exp_f32_e32 v172, v172
	v_exp_f32_e32 v173, v173
	v_exp_f32_e32 v174, v174
	v_exp_f32_e32 v175, v175
	v_exp_f32_e32 v176, v176
	v_exp_f32_e32 v177, v177
	v_pk_add_f32 v[170:171], v[170:171], 1.0 op_sel_hi:[1,0]
	v_pk_add_f32 v[172:173], v[172:173], 1.0 op_sel_hi:[1,0]
	v_pk_add_f32 v[174:175], v[174:175], 1.0 op_sel_hi:[1,0]
	v_pk_add_f32 v[176:177], v[176:177], 1.0 op_sel_hi:[1,0]
	v_rcp_f32_e32 v170, v170
	v_rcp_f32_e32 v171, v171
	v_rcp_f32_e32 v172, v172
	v_rcp_f32_e32 v173, v173
	v_rcp_f32_e32 v174, v174
	v_rcp_f32_e32 v175, v175
	v_rcp_f32_e32 v176, v176
	v_rcp_f32_e32 v177, v177
	v_pk_mul_f32 v[96:97], v[154:155], v[170:171]
	v_pk_mul_f32 v[98:99], v[156:157], v[172:173]
	v_pk_mul_f32 v[100:101], v[158:159], v[174:175]
	v_pk_mul_f32 v[102:103], v[160:161], v[176:177]
	v_pk_mul_f32 v[112:113], v[96:97], v[96:97]
	v_pk_mul_f32 v[114:115], v[98:99], v[98:99]
	v_pk_fma_f32 v[112:113], v[100:101], v[100:101], v[112:113]
	v_pk_fma_f32 v[114:115], v[102:103], v[102:103], v[114:115]
	v_pk_add_f32 v[112:113], v[112:113], v[114:115]
	v_add_f32_e32 v112, v112, v113
	v_pk_mul_f32 v[146:147], v[96:97], v[120:121]
	v_pk_mul_f32 v[148:149], v[98:99], v[122:123]
	v_add_f32_dpp v112, v112, v112 quad_perm:[1,0,3,2] row_mask:0xf bank_mask:0xf
	v_pk_mul_f32 v[150:151], v[100:101], v[124:125]
	v_pk_mul_f32 v[152:153], v[102:103], v[126:127]
	v_add_f32_dpp v112, v112, v112 quad_perm:[2,3,0,1] row_mask:0xf bank_mask:0xf
	s_nop 1
	v_add_f32_dpp v112, v112, v112 row_half_mirror row_mask:0xf bank_mask:0xf
	s_nop 1
	v_add_f32_dpp v112, v112, v112 row_mirror row_mask:0xf bank_mask:0xf
	s_nop 1
	v_readlane_b32 s98, v112, 0
	v_readlane_b32 s99, v112, 16
	v_readlane_b32 s100, v112, 32
	v_readlane_b32 vcc_lo, v112, 48
	s_nop 1
	v_mov_b32_e32 v113, s98
	v_add_f32_e32 v113, s99, v113
	v_add_f32_e32 v113, s100, v113
	v_add_f32_e32 v113, vcc_lo, v113
	v_fmamk_f32 v144, v113, 0x3b000000, v131
	v_rsq_f32_e32 v144, v144
	s_nop 0
	v_pk_mul_f32 v[146:147], v[146:147], v[144:145] op_sel_hi:[1,0]
	v_pk_mul_f32 v[148:149], v[148:149], v[144:145] op_sel_hi:[1,0]
	v_pk_mul_f32 v[150:151], v[150:151], v[144:145] op_sel_hi:[1,0]
	v_pk_mul_f32 v[152:153], v[152:153], v[144:145] op_sel_hi:[1,0]
	v_cvt_pk_bf16_f32 v116, v146, v147
	v_cvt_pk_bf16_f32 v117, v148, v149
	v_cvt_pk_bf16_f32 v118, v150, v151
	v_cvt_pk_bf16_f32 v119, v152, v153
	v_add_u32_e32 v138, 0x2c00000, v135
	global_store_dwordx4 v138, v[116:119], s[34:35]
	v_add_u32_e32 v136, 0x1e00000, v133
	v_add_u32_e32 v137, 0x6900000, v134
	global_load_dwordx4 v[36:39], v136, s[22:23] nt
	global_load_dwordx4 v[40:43], v136, s[20:21] nt
	global_load_dwordx4 v[44:47], v137, s[38:39] nt
	s_waitcnt vmcnt(12)
	v_lshlrev_b32_e32 v146, 16, v0
	v_and_b32_e32 v147, 0xffff0000, v0
	v_lshlrev_b32_e32 v148, 16, v1
	v_and_b32_e32 v149, 0xffff0000, v1
	v_lshlrev_b32_e32 v150, 16, v2
	v_and_b32_e32 v151, 0xffff0000, v2
	v_lshlrev_b32_e32 v152, 16, v3
	v_and_b32_e32 v153, 0xffff0000, v3
	v_lshlrev_b32_e32 v154, 16, v4
	v_and_b32_e32 v155, 0xffff0000, v4
	v_lshlrev_b32_e32 v156, 16, v5
	v_and_b32_e32 v157, 0xffff0000, v5
	v_lshlrev_b32_e32 v158, 16, v6
	v_and_b32_e32 v159, 0xffff0000, v6
	v_lshlrev_b32_e32 v160, 16, v7
	v_and_b32_e32 v161, 0xffff0000, v7
	v_lshlrev_b32_e32 v162, 16, v8
	v_and_b32_e32 v163, 0xffff0000, v8
	v_lshlrev_b32_e32 v164, 16, v9
	v_and_b32_e32 v165, 0xffff0000, v9
	v_lshlrev_b32_e32 v166, 16, v10
	v_and_b32_e32 v167, 0xffff0000, v10
	v_lshlrev_b32_e32 v168, 16, v11
	v_and_b32_e32 v169, 0xffff0000, v11
	v_pk_add_f32 v[146:147], v[146:147], v[154:155]
	v_pk_add_f32 v[148:149], v[148:149], v[156:157]
	v_pk_add_f32 v[150:151], v[150:151], v[158:159]
	v_pk_add_f32 v[152:153], v[152:153], v[160:161]
	v_pk_mul_f32 v[170:171], v[162:163], v[162:163]
	v_pk_mul_f32 v[172:173], v[164:165], v[164:165]
	v_pk_mul_f32 v[174:175], v[166:167], v[166:167]
	v_pk_mul_f32 v[176:177], v[168:169], v[168:169]
	v_pk_fma_f32 v[170:171], v[170:171], v[140:141], v[142:143] op_sel_hi:[1,0,0]
	v_pk_fma_f32 v[172:173], v[172:173], v[140:141], v[142:143] op_sel_hi:[1,0,0]
	v_pk_fma_f32 v[174:175], v[174:175], v[140:141], v[142:143] op_sel_hi:[1,0,0]
	v_pk_fma_f32 v[176:177], v[176:177], v[140:141], v[142:143] op_sel_hi:[1,0,0]
	v_pk_mul_f32 v[170:171], v[170:171], v[162:163]
	v_pk_mul_f32 v[172:173], v[172:173], v[164:165]
	v_pk_mul_f32 v[174:175], v[174:175], v[166:167]
	v_pk_mul_f32 v[176:177], v[176:177], v[168:169]
	v_pk_mul_f32 v[154:155], v[146:147], v[162:163]
	v_pk_mul_f32 v[156:157], v[148:149], v[164:165]
	v_pk_mul_f32 v[158:159], v[150:151], v[166:167]
	v_pk_mul_f32 v[160:161], v[152:153], v[168:169]
	v_exp_f32_e32 v170, v170
	v_exp_f32_e32 v171, v171
	v_exp_f32_e32 v172, v172
	v_exp_f32_e32 v173, v173
	v_exp_f32_e32 v174, v174
	v_exp_f32_e32 v175, v175
	v_exp_f32_e32 v176, v176
	v_exp_f32_e32 v177, v177
	v_pk_add_f32 v[170:171], v[170:171], 1.0 op_sel_hi:[1,0]
	v_pk_add_f32 v[172:173], v[172:173], 1.0 op_sel_hi:[1,0]
	v_pk_add_f32 v[174:175], v[174:175], 1.0 op_sel_hi:[1,0]
	v_pk_add_f32 v[176:177], v[176:177], 1.0 op_sel_hi:[1,0]
	v_rcp_f32_e32 v170, v170
	v_rcp_f32_e32 v171, v171
	v_rcp_f32_e32 v172, v172
	v_rcp_f32_e32 v173, v173
	v_rcp_f32_e32 v174, v174
	v_rcp_f32_e32 v175, v175
	v_rcp_f32_e32 v176, v176
	v_rcp_f32_e32 v177, v177
	v_pk_mul_f32 v[96:97], v[154:155], v[170:171]
	v_pk_mul_f32 v[98:99], v[156:157], v[172:173]
	v_pk_mul_f32 v[100:101], v[158:159], v[174:175]
	v_pk_mul_f32 v[102:103], v[160:161], v[176:177]
	v_pk_mul_f32 v[112:113], v[96:97], v[96:97]
	v_pk_mul_f32 v[114:115], v[98:99], v[98:99]
	v_pk_fma_f32 v[112:113], v[100:101], v[100:101], v[112:113]
	v_pk_fma_f32 v[114:115], v[102:103], v[102:103], v[114:115]
	v_pk_add_f32 v[112:113], v[112:113], v[114:115]
	v_add_f32_e32 v112, v112, v113
	v_pk_mul_f32 v[146:147], v[96:97], v[120:121]
	v_pk_mul_f32 v[148:149], v[98:99], v[122:123]
	v_add_f32_dpp v112, v112, v112 quad_perm:[1,0,3,2] row_mask:0xf bank_mask:0xf
	v_pk_mul_f32 v[150:151], v[100:101], v[124:125]
	v_pk_mul_f32 v[152:153], v[102:103], v[126:127]
	v_add_f32_dpp v112, v112, v112 quad_perm:[2,3,0,1] row_mask:0xf bank_mask:0xf
	s_nop 1
	v_add_f32_dpp v112, v112, v112 row_half_mirror row_mask:0xf bank_mask:0xf
	s_nop 1
	v_add_f32_dpp v112, v112, v112 row_mirror row_mask:0xf bank_mask:0xf
	s_nop 1
	v_readlane_b32 s98, v112, 0
	v_readlane_b32 s99, v112, 16
	v_readlane_b32 s100, v112, 32
	v_readlane_b32 vcc_lo, v112, 48
	s_nop 1
	v_mov_b32_e32 v113, s98
	v_add_f32_e32 v113, s99, v113
	v_add_f32_e32 v113, s100, v113
	v_add_f32_e32 v113, vcc_lo, v113
	v_fmamk_f32 v144, v113, 0x3b000000, v131
	v_rsq_f32_e32 v144, v144
	s_nop 0
	v_pk_mul_f32 v[146:147], v[146:147], v[144:145] op_sel_hi:[1,0]
	v_pk_mul_f32 v[148:149], v[148:149], v[144:145] op_sel_hi:[1,0]
	v_pk_mul_f32 v[150:151], v[150:151], v[144:145] op_sel_hi:[1,0]
	v_pk_mul_f32 v[152:153], v[152:153], v[144:145] op_sel_hi:[1,0]
	v_cvt_pk_bf16_f32 v116, v146, v147
	v_cvt_pk_bf16_f32 v117, v148, v149
	v_cvt_pk_bf16_f32 v118, v150, v151
	v_cvt_pk_bf16_f32 v119, v152, v153
	v_add_u32_e32 v138, 0x3000000, v135
	global_store_dwordx4 v138, v[116:119], s[34:35]
	s_waitcnt vmcnt(9)
	v_lshlrev_b32_e32 v146, 16, v12
	v_and_b32_e32 v147, 0xffff0000, v12
	v_lshlrev_b32_e32 v148, 16, v13
	v_and_b32_e32 v149, 0xffff0000, v13
	v_lshlrev_b32_e32 v150, 16, v14
	v_and_b32_e32 v151, 0xffff0000, v14
	v_lshlrev_b32_e32 v152, 16, v15
	v_and_b32_e32 v153, 0xffff0000, v15
	v_lshlrev_b32_e32 v154, 16, v16
	v_and_b32_e32 v155, 0xffff0000, v16
	v_lshlrev_b32_e32 v156, 16, v17
	v_and_b32_e32 v157, 0xffff0000, v17
	v_lshlrev_b32_e32 v158, 16, v18
	v_and_b32_e32 v159, 0xffff0000, v18
	v_lshlrev_b32_e32 v160, 16, v19
	v_and_b32_e32 v161, 0xffff0000, v19
	v_lshlrev_b32_e32 v162, 16, v20
	v_and_b32_e32 v163, 0xffff0000, v20
	v_lshlrev_b32_e32 v164, 16, v21
	v_and_b32_e32 v165, 0xffff0000, v21
	v_lshlrev_b32_e32 v166, 16, v22
	v_and_b32_e32 v167, 0xffff0000, v22
	v_lshlrev_b32_e32 v168, 16, v23
	v_and_b32_e32 v169, 0xffff0000, v23
	v_pk_add_f32 v[146:147], v[146:147], v[154:155]
	v_pk_add_f32 v[148:149], v[148:149], v[156:157]
	v_pk_add_f32 v[150:151], v[150:151], v[158:159]
	v_pk_add_f32 v[152:153], v[152:153], v[160:161]
	v_pk_mul_f32 v[170:171], v[162:163], v[162:163]
	v_pk_mul_f32 v[172:173], v[164:165], v[164:165]
	v_pk_mul_f32 v[174:175], v[166:167], v[166:167]
	v_pk_mul_f32 v[176:177], v[168:169], v[168:169]
	v_pk_fma_f32 v[170:171], v[170:171], v[140:141], v[142:143] op_sel_hi:[1,0,0]
	v_pk_fma_f32 v[172:173], v[172:173], v[140:141], v[142:143] op_sel_hi:[1,0,0]
	v_pk_fma_f32 v[174:175], v[174:175], v[140:141], v[142:143] op_sel_hi:[1,0,0]
	v_pk_fma_f32 v[176:177], v[176:177], v[140:141], v[142:143] op_sel_hi:[1,0,0]
	v_pk_mul_f32 v[170:171], v[170:171], v[162:163]
	v_pk_mul_f32 v[172:173], v[172:173], v[164:165]
	v_pk_mul_f32 v[174:175], v[174:175], v[166:167]
	v_pk_mul_f32 v[176:177], v[176:177], v[168:169]
	v_pk_mul_f32 v[154:155], v[146:147], v[162:163]
	v_pk_mul_f32 v[156:157], v[148:149], v[164:165]
	v_pk_mul_f32 v[158:159], v[150:151], v[166:167]
	v_pk_mul_f32 v[160:161], v[152:153], v[168:169]
	v_exp_f32_e32 v170, v170
	v_exp_f32_e32 v171, v171
	v_exp_f32_e32 v172, v172
	v_exp_f32_e32 v173, v173
	v_exp_f32_e32 v174, v174
	v_exp_f32_e32 v175, v175
	v_exp_f32_e32 v176, v176
	v_exp_f32_e32 v177, v177
	v_pk_add_f32 v[170:171], v[170:171], 1.0 op_sel_hi:[1,0]
	v_pk_add_f32 v[172:173], v[172:173], 1.0 op_sel_hi:[1,0]
	v_pk_add_f32 v[174:175], v[174:175], 1.0 op_sel_hi:[1,0]
	v_pk_add_f32 v[176:177], v[176:177], 1.0 op_sel_hi:[1,0]
	v_rcp_f32_e32 v170, v170
	v_rcp_f32_e32 v171, v171
	v_rcp_f32_e32 v172, v172
	v_rcp_f32_e32 v173, v173
	v_rcp_f32_e32 v174, v174
	v_rcp_f32_e32 v175, v175
	v_rcp_f32_e32 v176, v176
	v_rcp_f32_e32 v177, v177
	v_pk_mul_f32 v[96:97], v[154:155], v[170:171]
	v_pk_mul_f32 v[98:99], v[156:157], v[172:173]
	v_pk_mul_f32 v[100:101], v[158:159], v[174:175]
	v_pk_mul_f32 v[102:103], v[160:161], v[176:177]
	v_pk_mul_f32 v[112:113], v[96:97], v[96:97]
	v_pk_mul_f32 v[114:115], v[98:99], v[98:99]
	v_pk_fma_f32 v[112:113], v[100:101], v[100:101], v[112:113]
	v_pk_fma_f32 v[114:115], v[102:103], v[102:103], v[114:115]
	v_pk_add_f32 v[112:113], v[112:113], v[114:115]
	v_add_f32_e32 v112, v112, v113
	v_pk_mul_f32 v[146:147], v[96:97], v[120:121]
	v_pk_mul_f32 v[148:149], v[98:99], v[122:123]
	v_add_f32_dpp v112, v112, v112 quad_perm:[1,0,3,2] row_mask:0xf bank_mask:0xf
	v_pk_mul_f32 v[150:151], v[100:101], v[124:125]
	v_pk_mul_f32 v[152:153], v[102:103], v[126:127]
	v_add_f32_dpp v112, v112, v112 quad_perm:[2,3,0,1] row_mask:0xf bank_mask:0xf
	s_nop 1
	v_add_f32_dpp v112, v112, v112 row_half_mirror row_mask:0xf bank_mask:0xf
	s_nop 1
	v_add_f32_dpp v112, v112, v112 row_mirror row_mask:0xf bank_mask:0xf
	s_nop 1
	v_readlane_b32 s98, v112, 0
	v_readlane_b32 s99, v112, 16
	v_readlane_b32 s100, v112, 32
	v_readlane_b32 vcc_lo, v112, 48
	s_nop 1
	v_mov_b32_e32 v113, s98
	v_add_f32_e32 v113, s99, v113
	v_add_f32_e32 v113, s100, v113
	v_add_f32_e32 v113, vcc_lo, v113
	v_fmamk_f32 v144, v113, 0x3b000000, v131
	v_rsq_f32_e32 v144, v144
	s_nop 0
	v_pk_mul_f32 v[146:147], v[146:147], v[144:145] op_sel_hi:[1,0]
	v_pk_mul_f32 v[148:149], v[148:149], v[144:145] op_sel_hi:[1,0]
	v_pk_mul_f32 v[150:151], v[150:151], v[144:145] op_sel_hi:[1,0]
	v_pk_mul_f32 v[152:153], v[152:153], v[144:145] op_sel_hi:[1,0]
	v_cvt_pk_bf16_f32 v116, v146, v147
	v_cvt_pk_bf16_f32 v117, v148, v149
	v_cvt_pk_bf16_f32 v118, v150, v151
	v_cvt_pk_bf16_f32 v119, v152, v153
	v_add_u32_e32 v138, 0x3400000, v135
	global_store_dwordx4 v138, v[116:119], s[34:35]
	s_waitcnt vmcnt(6)
	v_lshlrev_b32_e32 v146, 16, v24
	v_and_b32_e32 v147, 0xffff0000, v24
	v_lshlrev_b32_e32 v148, 16, v25
	v_and_b32_e32 v149, 0xffff0000, v25
	v_lshlrev_b32_e32 v150, 16, v26
	v_and_b32_e32 v151, 0xffff0000, v26
	v_lshlrev_b32_e32 v152, 16, v27
	v_and_b32_e32 v153, 0xffff0000, v27
	v_lshlrev_b32_e32 v154, 16, v28
	v_and_b32_e32 v155, 0xffff0000, v28
	v_lshlrev_b32_e32 v156, 16, v29
	v_and_b32_e32 v157, 0xffff0000, v29
	v_lshlrev_b32_e32 v158, 16, v30
	v_and_b32_e32 v159, 0xffff0000, v30
	v_lshlrev_b32_e32 v160, 16, v31
	v_and_b32_e32 v161, 0xffff0000, v31
	v_lshlrev_b32_e32 v162, 16, v32
	v_and_b32_e32 v163, 0xffff0000, v32
	v_lshlrev_b32_e32 v164, 16, v33
	v_and_b32_e32 v165, 0xffff0000, v33
	v_lshlrev_b32_e32 v166, 16, v34
	v_and_b32_e32 v167, 0xffff0000, v34
	v_lshlrev_b32_e32 v168, 16, v35
	v_and_b32_e32 v169, 0xffff0000, v35
	v_pk_add_f32 v[146:147], v[146:147], v[154:155]
	v_pk_add_f32 v[148:149], v[148:149], v[156:157]
	v_pk_add_f32 v[150:151], v[150:151], v[158:159]
	v_pk_add_f32 v[152:153], v[152:153], v[160:161]
	v_pk_mul_f32 v[170:171], v[162:163], v[162:163]
	v_pk_mul_f32 v[172:173], v[164:165], v[164:165]
	v_pk_mul_f32 v[174:175], v[166:167], v[166:167]
	v_pk_mul_f32 v[176:177], v[168:169], v[168:169]
	v_pk_fma_f32 v[170:171], v[170:171], v[140:141], v[142:143] op_sel_hi:[1,0,0]
	v_pk_fma_f32 v[172:173], v[172:173], v[140:141], v[142:143] op_sel_hi:[1,0,0]
	v_pk_fma_f32 v[174:175], v[174:175], v[140:141], v[142:143] op_sel_hi:[1,0,0]
	v_pk_fma_f32 v[176:177], v[176:177], v[140:141], v[142:143] op_sel_hi:[1,0,0]
	v_pk_mul_f32 v[170:171], v[170:171], v[162:163]
	v_pk_mul_f32 v[172:173], v[172:173], v[164:165]
	v_pk_mul_f32 v[174:175], v[174:175], v[166:167]
	v_pk_mul_f32 v[176:177], v[176:177], v[168:169]
	v_pk_mul_f32 v[154:155], v[146:147], v[162:163]
	v_pk_mul_f32 v[156:157], v[148:149], v[164:165]
	v_pk_mul_f32 v[158:159], v[150:151], v[166:167]
	v_pk_mul_f32 v[160:161], v[152:153], v[168:169]
	v_exp_f32_e32 v170, v170
	v_exp_f32_e32 v171, v171
	v_exp_f32_e32 v172, v172
	v_exp_f32_e32 v173, v173
	v_exp_f32_e32 v174, v174
	v_exp_f32_e32 v175, v175
	v_exp_f32_e32 v176, v176
	v_exp_f32_e32 v177, v177
	v_pk_add_f32 v[170:171], v[170:171], 1.0 op_sel_hi:[1,0]
	v_pk_add_f32 v[172:173], v[172:173], 1.0 op_sel_hi:[1,0]
	v_pk_add_f32 v[174:175], v[174:175], 1.0 op_sel_hi:[1,0]
	v_pk_add_f32 v[176:177], v[176:177], 1.0 op_sel_hi:[1,0]
	v_rcp_f32_e32 v170, v170
	v_rcp_f32_e32 v171, v171
	v_rcp_f32_e32 v172, v172
	v_rcp_f32_e32 v173, v173
	v_rcp_f32_e32 v174, v174
	v_rcp_f32_e32 v175, v175
	v_rcp_f32_e32 v176, v176
	v_rcp_f32_e32 v177, v177
	v_pk_mul_f32 v[96:97], v[154:155], v[170:171]
	v_pk_mul_f32 v[98:99], v[156:157], v[172:173]
	v_pk_mul_f32 v[100:101], v[158:159], v[174:175]
	v_pk_mul_f32 v[102:103], v[160:161], v[176:177]
	v_pk_mul_f32 v[112:113], v[96:97], v[96:97]
	v_pk_mul_f32 v[114:115], v[98:99], v[98:99]
	v_pk_fma_f32 v[112:113], v[100:101], v[100:101], v[112:113]
	v_pk_fma_f32 v[114:115], v[102:103], v[102:103], v[114:115]
	v_pk_add_f32 v[112:113], v[112:113], v[114:115]
	v_add_f32_e32 v112, v112, v113
	v_pk_mul_f32 v[146:147], v[96:97], v[120:121]
	v_pk_mul_f32 v[148:149], v[98:99], v[122:123]
	v_add_f32_dpp v112, v112, v112 quad_perm:[1,0,3,2] row_mask:0xf bank_mask:0xf
	v_pk_mul_f32 v[150:151], v[100:101], v[124:125]
	v_pk_mul_f32 v[152:153], v[102:103], v[126:127]
	v_add_f32_dpp v112, v112, v112 quad_perm:[2,3,0,1] row_mask:0xf bank_mask:0xf
	s_nop 1
	v_add_f32_dpp v112, v112, v112 row_half_mirror row_mask:0xf bank_mask:0xf
	s_nop 1
	v_add_f32_dpp v112, v112, v112 row_mirror row_mask:0xf bank_mask:0xf
	s_nop 1
	v_readlane_b32 s98, v112, 0
	v_readlane_b32 s99, v112, 16
	v_readlane_b32 s100, v112, 32
	v_readlane_b32 vcc_lo, v112, 48
	s_nop 1
	v_mov_b32_e32 v113, s98
	v_add_f32_e32 v113, s99, v113
	v_add_f32_e32 v113, s100, v113
	v_add_f32_e32 v113, vcc_lo, v113
	v_fmamk_f32 v144, v113, 0x3b000000, v131
	v_rsq_f32_e32 v144, v144
	s_nop 0
	v_pk_mul_f32 v[146:147], v[146:147], v[144:145] op_sel_hi:[1,0]
	v_pk_mul_f32 v[148:149], v[148:149], v[144:145] op_sel_hi:[1,0]
	v_pk_mul_f32 v[150:151], v[150:151], v[144:145] op_sel_hi:[1,0]
	v_pk_mul_f32 v[152:153], v[152:153], v[144:145] op_sel_hi:[1,0]
	v_cvt_pk_bf16_f32 v116, v146, v147
	v_cvt_pk_bf16_f32 v117, v148, v149
	v_cvt_pk_bf16_f32 v118, v150, v151
	v_cvt_pk_bf16_f32 v119, v152, v153
	v_add_u32_e32 v138, 0x3800000, v135
	global_store_dwordx4 v138, v[116:119], s[34:35]
	s_waitcnt vmcnt(3)
	v_lshlrev_b32_e32 v146, 16, v36
	v_and_b32_e32 v147, 0xffff0000, v36
	v_lshlrev_b32_e32 v148, 16, v37
	v_and_b32_e32 v149, 0xffff0000, v37
	v_lshlrev_b32_e32 v150, 16, v38
	v_and_b32_e32 v151, 0xffff0000, v38
	v_lshlrev_b32_e32 v152, 16, v39
	v_and_b32_e32 v153, 0xffff0000, v39
	v_lshlrev_b32_e32 v154, 16, v40
	v_and_b32_e32 v155, 0xffff0000, v40
	v_lshlrev_b32_e32 v156, 16, v41
	v_and_b32_e32 v157, 0xffff0000, v41
	v_lshlrev_b32_e32 v158, 16, v42
	v_and_b32_e32 v159, 0xffff0000, v42
	v_lshlrev_b32_e32 v160, 16, v43
	v_and_b32_e32 v161, 0xffff0000, v43
	v_lshlrev_b32_e32 v162, 16, v44
	v_and_b32_e32 v163, 0xffff0000, v44
	v_lshlrev_b32_e32 v164, 16, v45
	v_and_b32_e32 v165, 0xffff0000, v45
	v_lshlrev_b32_e32 v166, 16, v46
	v_and_b32_e32 v167, 0xffff0000, v46
	v_lshlrev_b32_e32 v168, 16, v47
	v_and_b32_e32 v169, 0xffff0000, v47
	v_pk_add_f32 v[146:147], v[146:147], v[154:155]
	v_pk_add_f32 v[148:149], v[148:149], v[156:157]
	v_pk_add_f32 v[150:151], v[150:151], v[158:159]
	v_pk_add_f32 v[152:153], v[152:153], v[160:161]
	v_pk_mul_f32 v[170:171], v[162:163], v[162:163]
	v_pk_mul_f32 v[172:173], v[164:165], v[164:165]
	v_pk_mul_f32 v[174:175], v[166:167], v[166:167]
	v_pk_mul_f32 v[176:177], v[168:169], v[168:169]
	v_pk_fma_f32 v[170:171], v[170:171], v[140:141], v[142:143] op_sel_hi:[1,0,0]
	v_pk_fma_f32 v[172:173], v[172:173], v[140:141], v[142:143] op_sel_hi:[1,0,0]
	v_pk_fma_f32 v[174:175], v[174:175], v[140:141], v[142:143] op_sel_hi:[1,0,0]
	v_pk_fma_f32 v[176:177], v[176:177], v[140:141], v[142:143] op_sel_hi:[1,0,0]
	v_pk_mul_f32 v[170:171], v[170:171], v[162:163]
	v_pk_mul_f32 v[172:173], v[172:173], v[164:165]
	v_pk_mul_f32 v[174:175], v[174:175], v[166:167]
	v_pk_mul_f32 v[176:177], v[176:177], v[168:169]
	v_pk_mul_f32 v[154:155], v[146:147], v[162:163]
	v_pk_mul_f32 v[156:157], v[148:149], v[164:165]
	v_pk_mul_f32 v[158:159], v[150:151], v[166:167]
	v_pk_mul_f32 v[160:161], v[152:153], v[168:169]
	v_exp_f32_e32 v170, v170
	v_exp_f32_e32 v171, v171
	v_exp_f32_e32 v172, v172
	v_exp_f32_e32 v173, v173
	v_exp_f32_e32 v174, v174
	v_exp_f32_e32 v175, v175
	v_exp_f32_e32 v176, v176
	v_exp_f32_e32 v177, v177
	v_pk_add_f32 v[170:171], v[170:171], 1.0 op_sel_hi:[1,0]
	v_pk_add_f32 v[172:173], v[172:173], 1.0 op_sel_hi:[1,0]
	v_pk_add_f32 v[174:175], v[174:175], 1.0 op_sel_hi:[1,0]
	v_pk_add_f32 v[176:177], v[176:177], 1.0 op_sel_hi:[1,0]
	v_rcp_f32_e32 v170, v170
	v_rcp_f32_e32 v171, v171
	v_rcp_f32_e32 v172, v172
	v_rcp_f32_e32 v173, v173
	v_rcp_f32_e32 v174, v174
	v_rcp_f32_e32 v175, v175
	v_rcp_f32_e32 v176, v176
	v_rcp_f32_e32 v177, v177
	v_pk_mul_f32 v[96:97], v[154:155], v[170:171]
	v_pk_mul_f32 v[98:99], v[156:157], v[172:173]
	v_pk_mul_f32 v[100:101], v[158:159], v[174:175]
	v_pk_mul_f32 v[102:103], v[160:161], v[176:177]
	v_pk_mul_f32 v[112:113], v[96:97], v[96:97]
	v_pk_mul_f32 v[114:115], v[98:99], v[98:99]
	v_pk_fma_f32 v[112:113], v[100:101], v[100:101], v[112:113]
	v_pk_fma_f32 v[114:115], v[102:103], v[102:103], v[114:115]
	v_pk_add_f32 v[112:113], v[112:113], v[114:115]
	v_add_f32_e32 v112, v112, v113
	v_pk_mul_f32 v[146:147], v[96:97], v[120:121]
	v_pk_mul_f32 v[148:149], v[98:99], v[122:123]
	v_add_f32_dpp v112, v112, v112 quad_perm:[1,0,3,2] row_mask:0xf bank_mask:0xf
	v_pk_mul_f32 v[150:151], v[100:101], v[124:125]
	v_pk_mul_f32 v[152:153], v[102:103], v[126:127]
	v_add_f32_dpp v112, v112, v112 quad_perm:[2,3,0,1] row_mask:0xf bank_mask:0xf
	s_nop 1
	v_add_f32_dpp v112, v112, v112 row_half_mirror row_mask:0xf bank_mask:0xf
	s_nop 1
	v_add_f32_dpp v112, v112, v112 row_mirror row_mask:0xf bank_mask:0xf
	s_nop 1
	v_readlane_b32 s98, v112, 0
	v_readlane_b32 s99, v112, 16
	v_readlane_b32 s100, v112, 32
	v_readlane_b32 vcc_lo, v112, 48
	s_nop 1
	v_mov_b32_e32 v113, s98
	v_add_f32_e32 v113, s99, v113
	v_add_f32_e32 v113, s100, v113
	v_add_f32_e32 v113, vcc_lo, v113
	v_fmamk_f32 v144, v113, 0x3b000000, v131
	v_rsq_f32_e32 v144, v144
	s_nop 0
	v_pk_mul_f32 v[146:147], v[146:147], v[144:145] op_sel_hi:[1,0]
	v_pk_mul_f32 v[148:149], v[148:149], v[144:145] op_sel_hi:[1,0]
	v_pk_mul_f32 v[150:151], v[150:151], v[144:145] op_sel_hi:[1,0]
	v_pk_mul_f32 v[152:153], v[152:153], v[144:145] op_sel_hi:[1,0]
	v_cvt_pk_bf16_f32 v116, v146, v147
	v_cvt_pk_bf16_f32 v117, v148, v149
	v_cvt_pk_bf16_f32 v118, v150, v151
	v_cvt_pk_bf16_f32 v119, v152, v153
	v_add_u32_e32 v138, 0x3c00000, v135
	global_store_dwordx4 v138, v[116:119], s[34:35]
	s_cmp_eq_u32 s101, 0
	s_cbranch_scc1 .Lcomb_retA
	s_branch .Lcomb_retB
